# MO8 + loop-edge rotation: per-iteration pointer/counter/select SALU moved in front of the closing barrier of the K-loop
# baseline (speedup 1.0000x reference)
.LBB0_138:
	s_ashr_i32 s9, s8, 31
	s_lshl_b64 s[14:15], s[8:9], 21
	s_add_u32 s14, s88, s14
	s_addc_u32 s15, s89, s15
	s_and_b64 s[16:17], s[0:1], exec
	s_cselect_b32 s9, s15, s19
	s_cselect_b32 s44, s14, s18
	s_ashr_i32 s7, s6, 31
	s_lshl_b64 s[16:17], s[6:7], 21
	v_readlane_b32 s7, v255, 31
	s_add_u32 s16, s7, s16
	v_readlane_b32 s7, v255, 32
	s_addc_u32 s17, s7, s17
	s_and_b64 s[24:25], s[0:1], exec
	s_cselect_b32 s7, s17, s23
	s_cselect_b32 s45, s16, s22
	s_add_u32 s18, s18, 0x100080
	s_addc_u32 s19, s19, 0
	s_add_u32 s46, s22, 0x100
	v_mov_b32_e32 v2, 0
	s_addc_u32 s47, s23, 0
	s_mov_b32 s48, -2
	v_mov_b32_e32 v3, v2
	v_mov_b32_e32 v4, v2
	v_mov_b32_e32 v5, v2
	v_mov_b32_e32 v6, v2
	v_mov_b32_e32 v7, v2
	v_mov_b32_e32 v8, v2
	v_mov_b32_e32 v9, v2
	v_mov_b32_e32 v10, v2
	v_mov_b32_e32 v11, v2
	v_mov_b32_e32 v12, v2
	v_mov_b32_e32 v13, v2
	v_mov_b32_e32 v18, v2
	v_mov_b32_e32 v19, v2
	v_mov_b32_e32 v20, v2
	v_mov_b32_e32 v21, v2
	v_mov_b32_e32 v26, v2
	v_mov_b32_e32 v27, v2
	v_mov_b32_e32 v28, v2
	v_mov_b32_e32 v29, v2
	v_mov_b32_e32 v34, v2
	v_mov_b32_e32 v35, v2
	v_mov_b32_e32 v36, v2
	v_mov_b32_e32 v37, v2
	v_mov_b32_e32 v42, v2
	v_mov_b32_e32 v43, v2
	v_mov_b32_e32 v44, v2
	v_mov_b32_e32 v45, v2
	v_mov_b32_e32 v50, v2
	v_mov_b32_e32 v51, v2
	v_mov_b32_e32 v52, v2
	v_mov_b32_e32 v53, v2
	v_mov_b32_e32 v14, v2
	v_mov_b32_e32 v15, v2
	v_mov_b32_e32 v16, v2
	v_mov_b32_e32 v17, v2
	v_mov_b32_e32 v22, v2
	v_mov_b32_e32 v23, v2
	v_mov_b32_e32 v24, v2
	v_mov_b32_e32 v25, v2
	v_mov_b32_e32 v30, v2
	v_mov_b32_e32 v31, v2
	v_mov_b32_e32 v32, v2
	v_mov_b32_e32 v33, v2
	v_mov_b32_e32 v38, v2
	v_mov_b32_e32 v39, v2
	v_mov_b32_e32 v40, v2
	v_mov_b32_e32 v41, v2
	v_mov_b32_e32 v46, v2
	v_mov_b32_e32 v47, v2
	v_mov_b32_e32 v48, v2
	v_mov_b32_e32 v49, v2
	v_mov_b32_e32 v54, v2
	v_mov_b32_e32 v55, v2
	v_mov_b32_e32 v56, v2
	v_mov_b32_e32 v57, v2
	v_mov_b32_e32 v58, v2
	v_mov_b32_e32 v59, v2
	v_mov_b32_e32 v60, v2
	v_mov_b32_e32 v61, v2
	v_mov_b32_e32 v62, v2
	v_mov_b32_e32 v63, v2
	v_mov_b32_e32 v64, v2
	v_mov_b32_e32 v65, v2
	v_mov_b32_e32 v66, v2
	v_mov_b32_e32 v67, v2
	v_mov_b32_e32 v68, v2
	v_mov_b32_e32 v69, v2
	v_mov_b32_e32 v70, v2
	v_mov_b32_e32 v71, v2
	v_mov_b32_e32 v72, v2
	v_mov_b32_e32 v73, v2
	v_mov_b32_e32 v74, v2
	v_mov_b32_e32 v75, v2
	v_mov_b32_e32 v76, v2
	v_mov_b32_e32 v77, v2
	v_mov_b32_e32 v82, v2
	v_mov_b32_e32 v83, v2
	v_mov_b32_e32 v84, v2
	v_mov_b32_e32 v85, v2
	v_mov_b32_e32 v90, v2
	v_mov_b32_e32 v91, v2
	v_mov_b32_e32 v92, v2
	v_mov_b32_e32 v93, v2
	v_mov_b32_e32 v98, v2
	v_mov_b32_e32 v99, v2
	v_mov_b32_e32 v100, v2
	v_mov_b32_e32 v101, v2
	v_mov_b32_e32 v106, v2
	v_mov_b32_e32 v107, v2
	v_mov_b32_e32 v108, v2
	v_mov_b32_e32 v109, v2
	v_mov_b32_e32 v114, v2
	v_mov_b32_e32 v115, v2
	v_mov_b32_e32 v116, v2
	v_mov_b32_e32 v117, v2
	v_mov_b32_e32 v78, v2
	v_mov_b32_e32 v79, v2
	v_mov_b32_e32 v80, v2
	v_mov_b32_e32 v81, v2
	v_mov_b32_e32 v86, v2
	v_mov_b32_e32 v87, v2
	v_mov_b32_e32 v88, v2
	v_mov_b32_e32 v89, v2
	v_mov_b32_e32 v94, v2
	v_mov_b32_e32 v95, v2
	v_mov_b32_e32 v96, v2
	v_mov_b32_e32 v97, v2
	v_mov_b32_e32 v102, v2
	v_mov_b32_e32 v103, v2
	v_mov_b32_e32 v104, v2
	v_mov_b32_e32 v105, v2
	v_mov_b32_e32 v110, v2
	v_mov_b32_e32 v111, v2
	v_mov_b32_e32 v112, v2
	v_mov_b32_e32 v113, v2
	v_mov_b32_e32 v118, v2
	v_mov_b32_e32 v119, v2
	v_mov_b32_e32 v120, v2
	v_mov_b32_e32 v121, v2
	v_mov_b32_e32 v122, v2
	v_mov_b32_e32 v123, v2
	v_mov_b32_e32 v124, v2
	v_mov_b32_e32 v125, v2
	v_mov_b32_e32 v126, v2
	v_mov_b32_e32 v127, v2
	v_mov_b32_e32 v128, v2
	v_mov_b32_e32 v129, v2
	s_add_u32 s22, s18, 0xfff00080
	s_addc_u32 s23, s19, -1
	s_cmp_eq_u32 s48, 60
	s_cselect_b32 s25, s9, s23
	s_cselect_b32 s24, s44, s22
	s_cselect_b32 s23, s7, s47
	s_cselect_b32 s22, s45, s46
.LBB0_139:
	s_add_i32 s49, 0, 0x10000
	s_add_i32 s52, 0, 0x14000
	v_add_u32_e32 v156, s49, v145
	v_add_u32_e32 v172, s52, v145
	ds_read_b128 v[140:143], v156
	ds_read_b128 v[148:151], v156 offset:1024
	ds_read_b128 v[152:155], v156 offset:2048
	ds_read_b128 v[156:159], v156 offset:3072
	ds_read_b128 v[160:163], v172
	ds_read_b128 v[164:167], v172 offset:1024
	ds_read_b128 v[168:171], v172 offset:2048
	ds_read_b128 v[190:193], v172 offset:3072
	v_lshl_add_u64 v[172:173], s[18:19], 0, v[136:137]
	s_add_i32 m0, s31, 0xc000
	ds_read_b128 v[194:197], v147
	ds_read_b128 v[198:201], v147 offset:1024
	ds_read_b128 v[202:205], v147 offset:2048
	ds_read_b128 v[206:209], v147 offset:3072
	ds_read_b128 v[228:231], v147 offset:4096
	ds_read_b128 v[232:235], v147 offset:5120
	ds_read_b128 v[236:239], v147 offset:6144
	ds_read_b128 v[240:243], v147 offset:7168
	global_load_lds_dwordx4 v[172:173], off
	v_lshl_add_u64 v[172:173], s[18:19], 0, v[138:139]
	s_add_i32 m0, s31, 0xe000
	s_nop 0
	global_load_lds_dwordx4 v[172:173], off
	s_waitcnt vmcnt(8)
	s_waitcnt lgkmcnt(0)
	s_barrier
	s_setprio 1
	s_waitcnt lgkmcnt(0)
	v_mfma_f32_16x16x32_bf16 v[126:129], v[140:143], v[194:197], v[126:129]
	v_mfma_f32_16x16x32_bf16 v[126:129], v[148:151], v[198:201], v[126:129]
	v_mfma_f32_16x16x32_bf16 v[118:121], v[148:151], v[206:209], v[118:121]
	v_mfma_f32_16x16x32_bf16 v[118:121], v[140:143], v[202:205], v[118:121]
	v_mfma_f32_16x16x32_bf16 v[102:105], v[140:143], v[228:231], v[102:105]
	v_mfma_f32_16x16x32_bf16 v[102:105], v[148:151], v[232:235], v[102:105]
	v_mfma_f32_16x16x32_bf16 v[86:89], v[148:151], v[240:243], v[86:89]
	v_mfma_f32_16x16x32_bf16 v[86:89], v[140:143], v[236:239], v[86:89]
	v_mfma_f32_16x16x32_bf16 v[78:81], v[152:155], v[236:239], v[78:81]
	v_mfma_f32_16x16x32_bf16 v[78:81], v[156:159], v[240:243], v[78:81]
	v_mfma_f32_16x16x32_bf16 v[94:97], v[156:159], v[232:235], v[94:97]
	v_mfma_f32_16x16x32_bf16 v[94:97], v[152:155], v[228:231], v[94:97]
	v_mfma_f32_16x16x32_bf16 v[110:113], v[152:155], v[202:205], v[110:113]
	v_mfma_f32_16x16x32_bf16 v[110:113], v[156:159], v[206:209], v[110:113]
	v_mfma_f32_16x16x32_bf16 v[122:125], v[156:159], v[198:201], v[122:125]
	v_mfma_f32_16x16x32_bf16 v[122:125], v[152:155], v[194:197], v[122:125]
	s_setprio 0
	s_setprio 1
	v_mfma_f32_16x16x32_bf16 v[114:117], v[160:163], v[194:197], v[114:117]
	v_mfma_f32_16x16x32_bf16 v[114:117], v[164:167], v[198:201], v[114:117]
	v_mfma_f32_16x16x32_bf16 v[98:101], v[164:167], v[206:209], v[98:101]
	v_mfma_f32_16x16x32_bf16 v[98:101], v[160:163], v[202:205], v[98:101]
	v_mfma_f32_16x16x32_bf16 v[82:85], v[160:163], v[228:231], v[82:85]
	v_mfma_f32_16x16x32_bf16 v[82:85], v[164:167], v[232:235], v[82:85]
	v_mfma_f32_16x16x32_bf16 v[70:73], v[164:167], v[240:243], v[70:73]
	v_mfma_f32_16x16x32_bf16 v[70:73], v[160:163], v[236:239], v[70:73]
	v_mfma_f32_16x16x32_bf16 v[66:69], v[168:171], v[236:239], v[66:69]
	v_mfma_f32_16x16x32_bf16 v[66:69], v[190:193], v[240:243], v[66:69]
	v_mfma_f32_16x16x32_bf16 v[74:77], v[190:193], v[232:235], v[74:77]
	v_mfma_f32_16x16x32_bf16 v[74:77], v[168:171], v[228:231], v[74:77]
	v_mfma_f32_16x16x32_bf16 v[90:93], v[168:171], v[202:205], v[90:93]
	v_mfma_f32_16x16x32_bf16 v[90:93], v[190:193], v[206:209], v[90:93]
	v_mfma_f32_16x16x32_bf16 v[106:109], v[190:193], v[198:201], v[106:109]
	v_mfma_f32_16x16x32_bf16 v[106:109], v[168:171], v[194:197], v[106:109]
	s_setprio 0
	s_barrier
	s_add_i32 s49, s49, s26
	v_lshl_add_u64 v[172:173], s[22:23], 0, v[0:1]
	s_mov_b32 m0, s49
	ds_read_b128 v[194:197], v147 offset:16384
	ds_read_b128 v[198:201], v147 offset:17408
	ds_read_b128 v[202:205], v147 offset:18432
	ds_read_b128 v[206:209], v147 offset:19456
	ds_read_b128 v[228:231], v147 offset:20480
	ds_read_b128 v[232:235], v147 offset:21504
	ds_read_b128 v[236:239], v147 offset:22528
	ds_read_b128 v[240:243], v147 offset:23552
	global_load_lds_dwordx4 v[172:173], off
	s_add_i32 m0, s49, 0x2000
	s_add_u32 s50, s22, 0x100000
	v_lshl_add_u64 v[178:179], s[22:23], 0, v[130:131]
	s_addc_u32 s51, s23, 0
	s_add_i32 s49, s52, s26
	global_load_lds_dwordx4 v[178:179], off
	v_lshl_add_u64 v[180:181], s[50:51], 0, v[0:1]
	s_mov_b32 m0, s49
	v_lshl_add_u64 v[210:211], s[24:25], 0, v[132:133]
	global_load_lds_dwordx4 v[180:181], off
	v_lshl_add_u64 v[180:181], s[50:51], 0, v[130:131]
	s_add_i32 m0, s49, 0x2000
	s_nop 0
	global_load_lds_dwordx4 v[180:181], off
	v_lshl_add_u64 v[180:181], s[24:25], 0, v[134:135]
	s_mov_b32 m0, s31
	s_nop 0
	global_load_lds_dwordx4 v[180:181], off
	s_mov_b32 m0, s36
	s_nop 0
	global_load_lds_dwordx4 v[210:211], off
	s_waitcnt vmcnt(8)
	s_waitcnt lgkmcnt(0)
	s_barrier
	s_setprio 1
	s_waitcnt lgkmcnt(0)
	v_mfma_f32_16x16x32_bf16 v[62:65], v[140:143], v[194:197], v[62:65]
	v_mfma_f32_16x16x32_bf16 v[62:65], v[148:151], v[198:201], v[62:65]
	v_mfma_f32_16x16x32_bf16 v[54:57], v[148:151], v[206:209], v[54:57]
	v_mfma_f32_16x16x32_bf16 v[54:57], v[140:143], v[202:205], v[54:57]
	v_mfma_f32_16x16x32_bf16 v[38:41], v[140:143], v[228:231], v[38:41]
	v_mfma_f32_16x16x32_bf16 v[38:41], v[148:151], v[232:235], v[38:41]
	v_mfma_f32_16x16x32_bf16 v[22:25], v[148:151], v[240:243], v[22:25]
	v_mfma_f32_16x16x32_bf16 v[22:25], v[140:143], v[236:239], v[22:25]
	v_mfma_f32_16x16x32_bf16 v[14:17], v[152:155], v[236:239], v[14:17]
	v_mfma_f32_16x16x32_bf16 v[14:17], v[156:159], v[240:243], v[14:17]
	v_mfma_f32_16x16x32_bf16 v[30:33], v[156:159], v[232:235], v[30:33]
	v_mfma_f32_16x16x32_bf16 v[30:33], v[152:155], v[228:231], v[30:33]
	v_mfma_f32_16x16x32_bf16 v[46:49], v[152:155], v[202:205], v[46:49]
	v_mfma_f32_16x16x32_bf16 v[46:49], v[156:159], v[206:209], v[46:49]
	v_mfma_f32_16x16x32_bf16 v[58:61], v[156:159], v[198:201], v[58:61]
	v_mfma_f32_16x16x32_bf16 v[58:61], v[152:155], v[194:197], v[58:61]
	s_setprio 0
	s_setprio 1
	v_mfma_f32_16x16x32_bf16 v[50:53], v[160:163], v[194:197], v[50:53]
	v_mfma_f32_16x16x32_bf16 v[50:53], v[164:167], v[198:201], v[50:53]
	v_mfma_f32_16x16x32_bf16 v[34:37], v[164:167], v[206:209], v[34:37]
	v_mfma_f32_16x16x32_bf16 v[34:37], v[160:163], v[202:205], v[34:37]
	v_mfma_f32_16x16x32_bf16 v[18:21], v[160:163], v[228:231], v[18:21]
	v_mfma_f32_16x16x32_bf16 v[18:21], v[164:167], v[232:235], v[18:21]
	v_mfma_f32_16x16x32_bf16 v[6:9], v[164:167], v[240:243], v[6:9]
	v_mfma_f32_16x16x32_bf16 v[6:9], v[160:163], v[236:239], v[6:9]
	v_mfma_f32_16x16x32_bf16 v[2:5], v[168:171], v[236:239], v[2:5]
	v_mfma_f32_16x16x32_bf16 v[2:5], v[190:193], v[240:243], v[2:5]
	v_mfma_f32_16x16x32_bf16 v[10:13], v[190:193], v[232:235], v[10:13]
	v_mfma_f32_16x16x32_bf16 v[10:13], v[168:171], v[228:231], v[10:13]
	v_mfma_f32_16x16x32_bf16 v[26:29], v[168:171], v[202:205], v[26:29]
	v_mfma_f32_16x16x32_bf16 v[26:29], v[190:193], v[206:209], v[26:29]
	v_mfma_f32_16x16x32_bf16 v[42:45], v[190:193], v[198:201], v[42:45]
	v_mfma_f32_16x16x32_bf16 v[42:45], v[168:171], v[194:197], v[42:45]
	s_setprio 0
	s_barrier
	s_add_i32 s49, 0, 0x18000
	s_add_i32 s50, 0, 0x1c000
	v_add_u32_e32 v156, s49, v145
	v_add_u32_e32 v175, s50, v145
	ds_read_b128 v[140:143], v156
	ds_read_b128 v[148:151], v156 offset:1024
	ds_read_b128 v[152:155], v156 offset:2048
	ds_read_b128 v[156:159], v156 offset:3072
	ds_read_b128 v[160:163], v175
	ds_read_b128 v[164:167], v175 offset:1024
	ds_read_b128 v[168:171], v175 offset:2048
	ds_read_b128 v[190:193], v175 offset:3072
	s_add_u32 s24, s24, 0x100000
	s_addc_u32 s25, s25, 0
	s_mov_b32 m0, s37
	v_lshl_add_u64 v[244:245], s[24:25], 0, v[134:135]
	ds_read_b128 v[194:197], v147 offset:32768
	ds_read_b128 v[198:201], v147 offset:33792
	ds_read_b128 v[202:205], v147 offset:34816
	ds_read_b128 v[206:209], v147 offset:35840
	ds_read_b128 v[228:231], v147 offset:36864
	ds_read_b128 v[232:235], v147 offset:37888
	ds_read_b128 v[236:239], v147 offset:38912
	ds_read_b128 v[240:243], v147 offset:39936
	global_load_lds_dwordx4 v[244:245], off
	v_lshl_add_u64 v[244:245], s[24:25], 0, v[132:133]
	s_mov_b32 m0, s38
	s_nop 0
	global_load_lds_dwordx4 v[244:245], off
	s_waitcnt vmcnt(8)
	s_waitcnt lgkmcnt(0)
	s_barrier
	s_setprio 1
	s_waitcnt lgkmcnt(0)
	v_mfma_f32_16x16x32_bf16 v[126:129], v[140:143], v[194:197], v[126:129]
	v_mfma_f32_16x16x32_bf16 v[126:129], v[148:151], v[198:201], v[126:129]
	v_mfma_f32_16x16x32_bf16 v[118:121], v[148:151], v[206:209], v[118:121]
	v_mfma_f32_16x16x32_bf16 v[118:121], v[140:143], v[202:205], v[118:121]
	v_mfma_f32_16x16x32_bf16 v[102:105], v[140:143], v[228:231], v[102:105]
	v_mfma_f32_16x16x32_bf16 v[102:105], v[148:151], v[232:235], v[102:105]
	v_mfma_f32_16x16x32_bf16 v[86:89], v[148:151], v[240:243], v[86:89]
	v_mfma_f32_16x16x32_bf16 v[86:89], v[140:143], v[236:239], v[86:89]
	v_mfma_f32_16x16x32_bf16 v[78:81], v[152:155], v[236:239], v[78:81]
	v_mfma_f32_16x16x32_bf16 v[78:81], v[156:159], v[240:243], v[78:81]
	v_mfma_f32_16x16x32_bf16 v[94:97], v[156:159], v[232:235], v[94:97]
	v_mfma_f32_16x16x32_bf16 v[94:97], v[152:155], v[228:231], v[94:97]
	v_mfma_f32_16x16x32_bf16 v[110:113], v[152:155], v[202:205], v[110:113]
	v_mfma_f32_16x16x32_bf16 v[110:113], v[156:159], v[206:209], v[110:113]
	v_mfma_f32_16x16x32_bf16 v[122:125], v[156:159], v[198:201], v[122:125]
	v_mfma_f32_16x16x32_bf16 v[122:125], v[152:155], v[194:197], v[122:125]
	s_setprio 0
	s_setprio 1
	v_mfma_f32_16x16x32_bf16 v[114:117], v[160:163], v[194:197], v[114:117]
	v_mfma_f32_16x16x32_bf16 v[114:117], v[164:167], v[198:201], v[114:117]
	v_mfma_f32_16x16x32_bf16 v[98:101], v[164:167], v[206:209], v[98:101]
	v_mfma_f32_16x16x32_bf16 v[98:101], v[160:163], v[202:205], v[98:101]
	v_mfma_f32_16x16x32_bf16 v[82:85], v[160:163], v[228:231], v[82:85]
	v_mfma_f32_16x16x32_bf16 v[82:85], v[164:167], v[232:235], v[82:85]
	v_mfma_f32_16x16x32_bf16 v[70:73], v[164:167], v[240:243], v[70:73]
	v_mfma_f32_16x16x32_bf16 v[70:73], v[160:163], v[236:239], v[70:73]
	v_mfma_f32_16x16x32_bf16 v[66:69], v[168:171], v[236:239], v[66:69]
	v_mfma_f32_16x16x32_bf16 v[66:69], v[190:193], v[240:243], v[66:69]
	v_mfma_f32_16x16x32_bf16 v[74:77], v[190:193], v[232:235], v[74:77]
	v_mfma_f32_16x16x32_bf16 v[74:77], v[168:171], v[228:231], v[74:77]
	v_mfma_f32_16x16x32_bf16 v[90:93], v[168:171], v[202:205], v[90:93]
	v_mfma_f32_16x16x32_bf16 v[90:93], v[190:193], v[206:209], v[90:93]
	v_mfma_f32_16x16x32_bf16 v[106:109], v[190:193], v[198:201], v[106:109]
	v_mfma_f32_16x16x32_bf16 v[106:109], v[168:171], v[194:197], v[106:109]
	s_setprio 0
	s_barrier
	s_add_i32 s24, s49, s26
	v_lshl_add_u64 v[172:173], v[172:173], 0, s[34:35]
	s_mov_b32 m0, s24
	ds_read_b128 v[194:197], v147 offset:49152
	ds_read_b128 v[198:201], v147 offset:50176
	ds_read_b128 v[202:205], v147 offset:51200
	ds_read_b128 v[206:209], v147 offset:52224
	ds_read_b128 v[228:231], v147 offset:53248
	ds_read_b128 v[232:235], v147 offset:54272
	ds_read_b128 v[236:239], v147 offset:55296
	ds_read_b128 v[240:243], v147 offset:56320
	global_load_lds_dwordx4 v[172:173], off
	s_add_i32 m0, s24, 0x2000
	s_add_u32 s22, s22, 0x100080
	v_lshl_add_u64 v[172:173], v[178:179], 0, s[34:35]
	s_addc_u32 s23, s23, 0
	s_add_i32 s24, s50, s26
	global_load_lds_dwordx4 v[172:173], off
	v_lshl_add_u64 v[172:173], s[22:23], 0, v[0:1]
	s_mov_b32 m0, s24
	s_nop 0
	global_load_lds_dwordx4 v[172:173], off
	v_lshl_add_u64 v[172:173], s[22:23], 0, v[130:131]
	s_add_i32 m0, s24, 0x2000
	s_nop 0
	global_load_lds_dwordx4 v[172:173], off
	v_lshl_add_u64 v[172:173], v[180:181], 0, s[34:35]
	s_mov_b32 m0, s39
	s_nop 0
	global_load_lds_dwordx4 v[172:173], off
	v_lshl_add_u64 v[172:173], v[210:211], 0, s[34:35]
	s_mov_b32 m0, s40
	s_nop 0
	global_load_lds_dwordx4 v[172:173], off
	s_waitcnt vmcnt(8)
	s_waitcnt lgkmcnt(0)
	s_barrier
	s_setprio 1
	s_waitcnt lgkmcnt(0)
	v_mfma_f32_16x16x32_bf16 v[62:65], v[140:143], v[194:197], v[62:65]
	v_mfma_f32_16x16x32_bf16 v[62:65], v[148:151], v[198:201], v[62:65]
	v_mfma_f32_16x16x32_bf16 v[54:57], v[148:151], v[206:209], v[54:57]
	v_mfma_f32_16x16x32_bf16 v[54:57], v[140:143], v[202:205], v[54:57]
	v_mfma_f32_16x16x32_bf16 v[38:41], v[140:143], v[228:231], v[38:41]
	v_mfma_f32_16x16x32_bf16 v[38:41], v[148:151], v[232:235], v[38:41]
	v_mfma_f32_16x16x32_bf16 v[22:25], v[148:151], v[240:243], v[22:25]
	v_mfma_f32_16x16x32_bf16 v[22:25], v[140:143], v[236:239], v[22:25]
	v_mfma_f32_16x16x32_bf16 v[14:17], v[152:155], v[236:239], v[14:17]
	v_mfma_f32_16x16x32_bf16 v[14:17], v[156:159], v[240:243], v[14:17]
	v_mfma_f32_16x16x32_bf16 v[30:33], v[156:159], v[232:235], v[30:33]
	v_mfma_f32_16x16x32_bf16 v[30:33], v[152:155], v[228:231], v[30:33]
	v_mfma_f32_16x16x32_bf16 v[46:49], v[152:155], v[202:205], v[46:49]
	v_mfma_f32_16x16x32_bf16 v[46:49], v[156:159], v[206:209], v[46:49]
	v_mfma_f32_16x16x32_bf16 v[58:61], v[156:159], v[198:201], v[58:61]
	v_mfma_f32_16x16x32_bf16 v[58:61], v[152:155], v[194:197], v[58:61]
	s_setprio 0
	s_setprio 1
	v_mfma_f32_16x16x32_bf16 v[50:53], v[160:163], v[194:197], v[50:53]
	v_mfma_f32_16x16x32_bf16 v[50:53], v[164:167], v[198:201], v[50:53]
	v_mfma_f32_16x16x32_bf16 v[34:37], v[164:167], v[206:209], v[34:37]
	v_mfma_f32_16x16x32_bf16 v[34:37], v[160:163], v[202:205], v[34:37]
	v_mfma_f32_16x16x32_bf16 v[18:21], v[160:163], v[228:231], v[18:21]
	v_mfma_f32_16x16x32_bf16 v[18:21], v[164:167], v[232:235], v[18:21]
	v_mfma_f32_16x16x32_bf16 v[6:9], v[164:167], v[240:243], v[6:9]
	v_mfma_f32_16x16x32_bf16 v[6:9], v[160:163], v[236:239], v[6:9]
	v_mfma_f32_16x16x32_bf16 v[2:5], v[168:171], v[236:239], v[2:5]
	v_mfma_f32_16x16x32_bf16 v[2:5], v[190:193], v[240:243], v[2:5]
	v_mfma_f32_16x16x32_bf16 v[10:13], v[190:193], v[232:235], v[10:13]
	v_mfma_f32_16x16x32_bf16 v[10:13], v[168:171], v[228:231], v[10:13]
	v_mfma_f32_16x16x32_bf16 v[26:29], v[168:171], v[202:205], v[26:29]
	v_mfma_f32_16x16x32_bf16 v[26:29], v[190:193], v[206:209], v[26:29]
	v_mfma_f32_16x16x32_bf16 v[42:45], v[190:193], v[198:201], v[42:45]
	v_mfma_f32_16x16x32_bf16 v[42:45], v[168:171], v[194:197], v[42:45]
	s_add_i32 s48, s48, 2
	s_add_u32 s18, s18, 0x100
	s_addc_u32 s19, s19, 0
	s_add_u32 s46, s46, 0x100
	s_addc_u32 s47, s47, 0
	s_add_u32 s22, s18, 0xfff00080
	s_addc_u32 s23, s19, -1
	s_cmp_eq_u32 s48, 60
	s_cselect_b32 s25, s9, s23
	s_cselect_b32 s24, s44, s22
	s_cselect_b32 s23, s7, s47
	s_cselect_b32 s22, s45, s46
	s_cmp_gt_u32 s48, 61
	s_setprio 0
	s_barrier
	s_cbranch_scc0 .LBB0_139
	s_and_b64 vcc, exec, s[4:5]
	s_cbranch_vccz .LBB0_142
	s_barrier

.LBB0_574:
	s_ashr_i32 s9, s8, 31
	s_lshl_b64 s[14:15], s[8:9], 21
	v_readlane_b32 s7, v254, 15
	s_add_u32 s14, s7, s14
	v_readlane_b32 s7, v254, 16
	s_addc_u32 s15, s7, s15
	s_and_b64 s[16:17], s[0:1], exec
	s_cselect_b32 s9, s15, s19
	s_cselect_b32 s48, s14, s18
	s_ashr_i32 s7, s6, 31
	s_lshl_b64 s[16:17], s[6:7], 21
	s_add_u32 s16, s26, s16
	s_addc_u32 s17, s31, s17
	s_and_b64 s[24:25], s[0:1], exec
	s_cselect_b32 s7, s17, s23
	s_cselect_b32 s49, s16, s22
	s_add_u32 s18, s18, 0x100080
	s_addc_u32 s19, s19, 0
	s_add_u32 s50, s22, 0x100
	v_mov_b32_e32 v2, 0
	s_addc_u32 s51, s23, 0
	s_mov_b32 s52, -2
	v_mov_b32_e32 v3, v2
	v_mov_b32_e32 v4, v2
	v_mov_b32_e32 v5, v2
	v_mov_b32_e32 v6, v2
	v_mov_b32_e32 v7, v2
	v_mov_b32_e32 v8, v2
	v_mov_b32_e32 v9, v2
	v_mov_b32_e32 v10, v2
	v_mov_b32_e32 v11, v2
	v_mov_b32_e32 v12, v2
	v_mov_b32_e32 v13, v2
	v_mov_b32_e32 v18, v2
	v_mov_b32_e32 v19, v2
	v_mov_b32_e32 v20, v2
	v_mov_b32_e32 v21, v2
	v_mov_b32_e32 v26, v2
	v_mov_b32_e32 v27, v2
	v_mov_b32_e32 v28, v2
	v_mov_b32_e32 v29, v2
	v_mov_b32_e32 v34, v2
	v_mov_b32_e32 v35, v2
	v_mov_b32_e32 v36, v2
	v_mov_b32_e32 v37, v2
	v_mov_b32_e32 v42, v2
	v_mov_b32_e32 v43, v2
	v_mov_b32_e32 v44, v2
	v_mov_b32_e32 v45, v2
	v_mov_b32_e32 v50, v2
	v_mov_b32_e32 v51, v2
	v_mov_b32_e32 v52, v2
	v_mov_b32_e32 v53, v2
	v_mov_b32_e32 v14, v2
	v_mov_b32_e32 v15, v2
	v_mov_b32_e32 v16, v2
	v_mov_b32_e32 v17, v2
	v_mov_b32_e32 v22, v2
	v_mov_b32_e32 v23, v2
	v_mov_b32_e32 v24, v2
	v_mov_b32_e32 v25, v2
	v_mov_b32_e32 v30, v2
	v_mov_b32_e32 v31, v2
	v_mov_b32_e32 v32, v2
	v_mov_b32_e32 v33, v2
	v_mov_b32_e32 v38, v2
	v_mov_b32_e32 v39, v2
	v_mov_b32_e32 v40, v2
	v_mov_b32_e32 v41, v2
	v_mov_b32_e32 v46, v2
	v_mov_b32_e32 v47, v2
	v_mov_b32_e32 v48, v2
	v_mov_b32_e32 v49, v2
	v_mov_b32_e32 v54, v2
	v_mov_b32_e32 v55, v2
	v_mov_b32_e32 v56, v2
	v_mov_b32_e32 v57, v2
	v_mov_b32_e32 v58, v2
	v_mov_b32_e32 v59, v2
	v_mov_b32_e32 v60, v2
	v_mov_b32_e32 v61, v2
	v_mov_b32_e32 v62, v2
	v_mov_b32_e32 v63, v2
	v_mov_b32_e32 v64, v2
	v_mov_b32_e32 v65, v2
	v_mov_b32_e32 v66, v2
	v_mov_b32_e32 v67, v2
	v_mov_b32_e32 v68, v2
	v_mov_b32_e32 v69, v2
	v_mov_b32_e32 v70, v2
	v_mov_b32_e32 v71, v2
	v_mov_b32_e32 v72, v2
	v_mov_b32_e32 v73, v2
	v_mov_b32_e32 v74, v2
	v_mov_b32_e32 v75, v2
	v_mov_b32_e32 v76, v2
	v_mov_b32_e32 v77, v2
	v_mov_b32_e32 v82, v2
	v_mov_b32_e32 v83, v2
	v_mov_b32_e32 v84, v2
	v_mov_b32_e32 v85, v2
	v_mov_b32_e32 v90, v2
	v_mov_b32_e32 v91, v2
	v_mov_b32_e32 v92, v2
	v_mov_b32_e32 v93, v2
	v_mov_b32_e32 v98, v2
	v_mov_b32_e32 v99, v2
	v_mov_b32_e32 v100, v2
	v_mov_b32_e32 v101, v2
	v_mov_b32_e32 v106, v2
	v_mov_b32_e32 v107, v2
	v_mov_b32_e32 v108, v2
	v_mov_b32_e32 v109, v2
	v_mov_b32_e32 v114, v2
	v_mov_b32_e32 v115, v2
	v_mov_b32_e32 v116, v2
	v_mov_b32_e32 v117, v2
	v_mov_b32_e32 v78, v2
	v_mov_b32_e32 v79, v2
	v_mov_b32_e32 v80, v2
	v_mov_b32_e32 v81, v2
	v_mov_b32_e32 v86, v2
	v_mov_b32_e32 v87, v2
	v_mov_b32_e32 v88, v2
	v_mov_b32_e32 v89, v2
	v_mov_b32_e32 v94, v2
	v_mov_b32_e32 v95, v2
	v_mov_b32_e32 v96, v2
	v_mov_b32_e32 v97, v2
	v_mov_b32_e32 v102, v2
	v_mov_b32_e32 v103, v2
	v_mov_b32_e32 v104, v2
	v_mov_b32_e32 v105, v2
	v_mov_b32_e32 v110, v2
	v_mov_b32_e32 v111, v2
	v_mov_b32_e32 v112, v2
	v_mov_b32_e32 v113, v2
	v_mov_b32_e32 v118, v2
	v_mov_b32_e32 v119, v2
	v_mov_b32_e32 v120, v2
	v_mov_b32_e32 v121, v2
	v_mov_b32_e32 v122, v2
	v_mov_b32_e32 v123, v2
	v_mov_b32_e32 v124, v2
	v_mov_b32_e32 v125, v2
	v_mov_b32_e32 v126, v2
	v_mov_b32_e32 v127, v2
	v_mov_b32_e32 v128, v2
	v_mov_b32_e32 v129, v2
	s_add_u32 s22, s18, 0xfff00080
	s_addc_u32 s23, s19, -1
	s_cmp_eq_u32 s52, 60
	s_cselect_b32 s25, s9, s23
	s_cselect_b32 s24, s48, s22
	s_cselect_b32 s23, s7, s51
	s_cselect_b32 s22, s49, s50
.LBB0_575:
	s_add_i32 s53, 0, 0x10000
	v_add_u32_e32 v140, s53, v143
	s_add_i32 s56, 0, 0x14000
	ds_read_b128 v[146:149], v140
	ds_read_b128 v[150:153], v140 offset:1024
	ds_read_b128 v[154:157], v140 offset:2048
	ds_read_b128 v[158:161], v140 offset:3072
	v_add_u32_e32 v140, s56, v143
	ds_read_b128 v[162:165], v140
	ds_read_b128 v[166:169], v140 offset:1024
	ds_read_b128 v[170:173], v140 offset:2048
	ds_read_b128 v[178:181], v140 offset:3072
	v_lshl_add_u64 v[140:141], s[18:19], 0, v[136:137]
	s_add_i32 m0, s39, 0xc000
	ds_read_b128 v[190:193], v145
	ds_read_b128 v[194:197], v145 offset:1024
	ds_read_b128 v[198:201], v145 offset:2048
	ds_read_b128 v[202:205], v145 offset:3072
	ds_read_b128 v[206:209], v145 offset:4096
	ds_read_b128 v[228:231], v145 offset:5120
	ds_read_b128 v[232:235], v145 offset:6144
	ds_read_b128 v[236:239], v145 offset:7168
	global_load_lds_dwordx4 v[140:141], off
	v_lshl_add_u64 v[140:141], s[18:19], 0, v[138:139]
	s_add_i32 m0, s39, 0xe000
	s_nop 0
	global_load_lds_dwordx4 v[140:141], off
	s_waitcnt vmcnt(8)
	s_waitcnt lgkmcnt(0)
	s_barrier
	s_setprio 1
	s_waitcnt lgkmcnt(0)
	v_mfma_f32_16x16x32_bf16 v[126:129], v[146:149], v[190:193], v[126:129]
	v_mfma_f32_16x16x32_bf16 v[126:129], v[150:153], v[194:197], v[126:129]
	v_mfma_f32_16x16x32_bf16 v[118:121], v[150:153], v[202:205], v[118:121]
	v_mfma_f32_16x16x32_bf16 v[118:121], v[146:149], v[198:201], v[118:121]
	v_mfma_f32_16x16x32_bf16 v[102:105], v[146:149], v[206:209], v[102:105]
	v_mfma_f32_16x16x32_bf16 v[102:105], v[150:153], v[228:231], v[102:105]
	v_mfma_f32_16x16x32_bf16 v[86:89], v[150:153], v[236:239], v[86:89]
	v_mfma_f32_16x16x32_bf16 v[86:89], v[146:149], v[232:235], v[86:89]
	v_mfma_f32_16x16x32_bf16 v[78:81], v[154:157], v[232:235], v[78:81]
	v_mfma_f32_16x16x32_bf16 v[78:81], v[158:161], v[236:239], v[78:81]
	v_mfma_f32_16x16x32_bf16 v[94:97], v[158:161], v[228:231], v[94:97]
	v_mfma_f32_16x16x32_bf16 v[94:97], v[154:157], v[206:209], v[94:97]
	v_mfma_f32_16x16x32_bf16 v[110:113], v[154:157], v[198:201], v[110:113]
	v_mfma_f32_16x16x32_bf16 v[110:113], v[158:161], v[202:205], v[110:113]
	v_mfma_f32_16x16x32_bf16 v[122:125], v[158:161], v[194:197], v[122:125]
	v_mfma_f32_16x16x32_bf16 v[122:125], v[154:157], v[190:193], v[122:125]
	s_setprio 0
	s_setprio 1
	v_mfma_f32_16x16x32_bf16 v[114:117], v[162:165], v[190:193], v[114:117]
	v_mfma_f32_16x16x32_bf16 v[114:117], v[166:169], v[194:197], v[114:117]
	v_mfma_f32_16x16x32_bf16 v[98:101], v[166:169], v[202:205], v[98:101]
	v_mfma_f32_16x16x32_bf16 v[98:101], v[162:165], v[198:201], v[98:101]
	v_mfma_f32_16x16x32_bf16 v[82:85], v[162:165], v[206:209], v[82:85]
	v_mfma_f32_16x16x32_bf16 v[82:85], v[166:169], v[228:231], v[82:85]
	v_mfma_f32_16x16x32_bf16 v[70:73], v[166:169], v[236:239], v[70:73]
	v_mfma_f32_16x16x32_bf16 v[70:73], v[162:165], v[232:235], v[70:73]
	v_mfma_f32_16x16x32_bf16 v[66:69], v[170:173], v[232:235], v[66:69]
	v_mfma_f32_16x16x32_bf16 v[66:69], v[178:181], v[236:239], v[66:69]
	v_mfma_f32_16x16x32_bf16 v[74:77], v[178:181], v[228:231], v[74:77]
	v_mfma_f32_16x16x32_bf16 v[74:77], v[170:173], v[206:209], v[74:77]
	v_mfma_f32_16x16x32_bf16 v[90:93], v[170:173], v[198:201], v[90:93]
	v_mfma_f32_16x16x32_bf16 v[90:93], v[178:181], v[202:205], v[90:93]
	v_mfma_f32_16x16x32_bf16 v[106:109], v[178:181], v[194:197], v[106:109]
	v_mfma_f32_16x16x32_bf16 v[106:109], v[170:173], v[190:193], v[106:109]
	s_setprio 0
	s_barrier
	s_add_i32 s53, s53, s38
	v_lshl_add_u64 v[140:141], s[22:23], 0, v[0:1]
	s_mov_b32 m0, s53
	ds_read_b128 v[190:193], v145 offset:16384
	ds_read_b128 v[194:197], v145 offset:17408
	ds_read_b128 v[198:201], v145 offset:18432
	ds_read_b128 v[202:205], v145 offset:19456
	ds_read_b128 v[206:209], v145 offset:20480
	ds_read_b128 v[228:231], v145 offset:21504
	ds_read_b128 v[232:235], v145 offset:22528
	ds_read_b128 v[236:239], v145 offset:23552
	global_load_lds_dwordx4 v[140:141], off
	s_add_i32 m0, s53, 0x2000
	s_add_u32 s54, s22, 0x100000
	v_lshl_add_u64 v[186:187], s[22:23], 0, v[130:131]
	s_addc_u32 s55, s23, 0
	s_add_i32 s53, s56, s38
	global_load_lds_dwordx4 v[186:187], off
	v_lshl_add_u64 v[188:189], s[54:55], 0, v[0:1]
	s_mov_b32 m0, s53
	v_lshl_add_u64 v[210:211], s[24:25], 0, v[132:133]
	global_load_lds_dwordx4 v[188:189], off
	v_lshl_add_u64 v[188:189], s[54:55], 0, v[130:131]
	s_add_i32 m0, s53, 0x2000
	s_nop 0
	global_load_lds_dwordx4 v[188:189], off
	v_lshl_add_u64 v[188:189], s[24:25], 0, v[134:135]
	s_mov_b32 m0, s39
	s_nop 0
	global_load_lds_dwordx4 v[188:189], off
	s_mov_b32 m0, s40
	s_nop 0
	global_load_lds_dwordx4 v[210:211], off
	s_waitcnt vmcnt(8)
	s_waitcnt lgkmcnt(0)
	s_barrier
	s_setprio 1
	s_waitcnt lgkmcnt(0)
	v_mfma_f32_16x16x32_bf16 v[62:65], v[146:149], v[190:193], v[62:65]
	v_mfma_f32_16x16x32_bf16 v[62:65], v[150:153], v[194:197], v[62:65]
	v_mfma_f32_16x16x32_bf16 v[54:57], v[150:153], v[202:205], v[54:57]
	v_mfma_f32_16x16x32_bf16 v[54:57], v[146:149], v[198:201], v[54:57]
	v_mfma_f32_16x16x32_bf16 v[38:41], v[146:149], v[206:209], v[38:41]
	v_mfma_f32_16x16x32_bf16 v[38:41], v[150:153], v[228:231], v[38:41]
	v_mfma_f32_16x16x32_bf16 v[22:25], v[150:153], v[236:239], v[22:25]
	v_mfma_f32_16x16x32_bf16 v[22:25], v[146:149], v[232:235], v[22:25]
	v_mfma_f32_16x16x32_bf16 v[14:17], v[154:157], v[232:235], v[14:17]
	v_mfma_f32_16x16x32_bf16 v[14:17], v[158:161], v[236:239], v[14:17]
	v_mfma_f32_16x16x32_bf16 v[30:33], v[158:161], v[228:231], v[30:33]
	v_mfma_f32_16x16x32_bf16 v[30:33], v[154:157], v[206:209], v[30:33]
	v_mfma_f32_16x16x32_bf16 v[46:49], v[154:157], v[198:201], v[46:49]
	v_mfma_f32_16x16x32_bf16 v[46:49], v[158:161], v[202:205], v[46:49]
	v_mfma_f32_16x16x32_bf16 v[58:61], v[158:161], v[194:197], v[58:61]
	v_mfma_f32_16x16x32_bf16 v[58:61], v[154:157], v[190:193], v[58:61]
	s_setprio 0
	s_setprio 1
	v_mfma_f32_16x16x32_bf16 v[50:53], v[162:165], v[190:193], v[50:53]
	v_mfma_f32_16x16x32_bf16 v[50:53], v[166:169], v[194:197], v[50:53]
	v_mfma_f32_16x16x32_bf16 v[34:37], v[166:169], v[202:205], v[34:37]
	v_mfma_f32_16x16x32_bf16 v[34:37], v[162:165], v[198:201], v[34:37]
	v_mfma_f32_16x16x32_bf16 v[18:21], v[162:165], v[206:209], v[18:21]
	v_mfma_f32_16x16x32_bf16 v[18:21], v[166:169], v[228:231], v[18:21]
	v_mfma_f32_16x16x32_bf16 v[6:9], v[166:169], v[236:239], v[6:9]
	v_mfma_f32_16x16x32_bf16 v[6:9], v[162:165], v[232:235], v[6:9]
	v_mfma_f32_16x16x32_bf16 v[2:5], v[170:173], v[232:235], v[2:5]
	v_mfma_f32_16x16x32_bf16 v[2:5], v[178:181], v[236:239], v[2:5]
	v_mfma_f32_16x16x32_bf16 v[10:13], v[178:181], v[228:231], v[10:13]
	v_mfma_f32_16x16x32_bf16 v[10:13], v[170:173], v[206:209], v[10:13]
	v_mfma_f32_16x16x32_bf16 v[26:29], v[170:173], v[198:201], v[26:29]
	v_mfma_f32_16x16x32_bf16 v[26:29], v[178:181], v[202:205], v[26:29]
	v_mfma_f32_16x16x32_bf16 v[42:45], v[178:181], v[194:197], v[42:45]
	v_mfma_f32_16x16x32_bf16 v[42:45], v[170:173], v[190:193], v[42:45]
	s_setprio 0
	s_barrier
	s_add_i32 s53, 0, 0x18000
	s_add_i32 s54, 0, 0x1c000
	v_add_u32_e32 v158, s53, v143
	v_add_u32_e32 v175, s54, v143
	ds_read_b128 v[146:149], v158
	ds_read_b128 v[150:153], v158 offset:1024
	ds_read_b128 v[154:157], v158 offset:2048
	ds_read_b128 v[158:161], v158 offset:3072
	ds_read_b128 v[162:165], v175
	ds_read_b128 v[166:169], v175 offset:1024
	ds_read_b128 v[170:173], v175 offset:2048
	ds_read_b128 v[178:181], v175 offset:3072
	s_add_u32 s24, s24, 0x100000
	s_addc_u32 s25, s25, 0
	s_mov_b32 m0, s41
	v_lshl_add_u64 v[226:227], s[24:25], 0, v[134:135]
	ds_read_b128 v[190:193], v145 offset:32768
	ds_read_b128 v[194:197], v145 offset:33792
	ds_read_b128 v[198:201], v145 offset:34816
	ds_read_b128 v[202:205], v145 offset:35840
	ds_read_b128 v[206:209], v145 offset:36864
	ds_read_b128 v[228:231], v145 offset:37888
	ds_read_b128 v[232:235], v145 offset:38912
	ds_read_b128 v[236:239], v145 offset:39936
	global_load_lds_dwordx4 v[226:227], off
	v_lshl_add_u64 v[226:227], s[24:25], 0, v[132:133]
	s_mov_b32 m0, s42
	s_nop 0
	global_load_lds_dwordx4 v[226:227], off
	s_waitcnt vmcnt(8)
	s_waitcnt lgkmcnt(0)
	s_barrier
	s_setprio 1
	s_waitcnt lgkmcnt(0)
	v_mfma_f32_16x16x32_bf16 v[126:129], v[146:149], v[190:193], v[126:129]
	v_mfma_f32_16x16x32_bf16 v[126:129], v[150:153], v[194:197], v[126:129]
	v_mfma_f32_16x16x32_bf16 v[118:121], v[150:153], v[202:205], v[118:121]
	v_mfma_f32_16x16x32_bf16 v[118:121], v[146:149], v[198:201], v[118:121]
	v_mfma_f32_16x16x32_bf16 v[102:105], v[146:149], v[206:209], v[102:105]
	v_mfma_f32_16x16x32_bf16 v[102:105], v[150:153], v[228:231], v[102:105]
	v_mfma_f32_16x16x32_bf16 v[86:89], v[150:153], v[236:239], v[86:89]
	v_mfma_f32_16x16x32_bf16 v[86:89], v[146:149], v[232:235], v[86:89]
	v_mfma_f32_16x16x32_bf16 v[78:81], v[154:157], v[232:235], v[78:81]
	v_mfma_f32_16x16x32_bf16 v[78:81], v[158:161], v[236:239], v[78:81]
	v_mfma_f32_16x16x32_bf16 v[94:97], v[158:161], v[228:231], v[94:97]
	v_mfma_f32_16x16x32_bf16 v[94:97], v[154:157], v[206:209], v[94:97]
	v_mfma_f32_16x16x32_bf16 v[110:113], v[154:157], v[198:201], v[110:113]
	v_mfma_f32_16x16x32_bf16 v[110:113], v[158:161], v[202:205], v[110:113]
	v_mfma_f32_16x16x32_bf16 v[122:125], v[158:161], v[194:197], v[122:125]
	v_mfma_f32_16x16x32_bf16 v[122:125], v[154:157], v[190:193], v[122:125]
	s_setprio 0
	s_setprio 1
	v_mfma_f32_16x16x32_bf16 v[114:117], v[162:165], v[190:193], v[114:117]
	v_mfma_f32_16x16x32_bf16 v[114:117], v[166:169], v[194:197], v[114:117]
	v_mfma_f32_16x16x32_bf16 v[98:101], v[166:169], v[202:205], v[98:101]
	v_mfma_f32_16x16x32_bf16 v[98:101], v[162:165], v[198:201], v[98:101]
	v_mfma_f32_16x16x32_bf16 v[82:85], v[162:165], v[206:209], v[82:85]
	v_mfma_f32_16x16x32_bf16 v[82:85], v[166:169], v[228:231], v[82:85]
	v_mfma_f32_16x16x32_bf16 v[70:73], v[166:169], v[236:239], v[70:73]
	v_mfma_f32_16x16x32_bf16 v[70:73], v[162:165], v[232:235], v[70:73]
	v_mfma_f32_16x16x32_bf16 v[66:69], v[170:173], v[232:235], v[66:69]
	v_mfma_f32_16x16x32_bf16 v[66:69], v[178:181], v[236:239], v[66:69]
	v_mfma_f32_16x16x32_bf16 v[74:77], v[178:181], v[228:231], v[74:77]
	v_mfma_f32_16x16x32_bf16 v[74:77], v[170:173], v[206:209], v[74:77]
	v_mfma_f32_16x16x32_bf16 v[90:93], v[170:173], v[198:201], v[90:93]
	v_mfma_f32_16x16x32_bf16 v[90:93], v[178:181], v[202:205], v[90:93]
	v_mfma_f32_16x16x32_bf16 v[106:109], v[178:181], v[194:197], v[106:109]
	v_mfma_f32_16x16x32_bf16 v[106:109], v[170:173], v[190:193], v[106:109]
	s_setprio 0
	s_barrier
	s_add_i32 s24, s53, s38
	v_lshl_add_u64 v[140:141], v[140:141], 0, s[34:35]
	s_mov_b32 m0, s24
	ds_read_b128 v[190:193], v145 offset:49152
	ds_read_b128 v[194:197], v145 offset:50176
	ds_read_b128 v[198:201], v145 offset:51200
	ds_read_b128 v[202:205], v145 offset:52224
	ds_read_b128 v[206:209], v145 offset:53248
	ds_read_b128 v[228:231], v145 offset:54272
	ds_read_b128 v[232:235], v145 offset:55296
	ds_read_b128 v[236:239], v145 offset:56320
	global_load_lds_dwordx4 v[140:141], off
	s_add_i32 m0, s24, 0x2000
	s_add_u32 s22, s22, 0x100080
	v_lshl_add_u64 v[140:141], v[186:187], 0, s[34:35]
	s_addc_u32 s23, s23, 0
	s_add_i32 s24, s54, s38
	global_load_lds_dwordx4 v[140:141], off
	v_lshl_add_u64 v[140:141], s[22:23], 0, v[0:1]
	s_mov_b32 m0, s24
	s_nop 0
	global_load_lds_dwordx4 v[140:141], off
	v_lshl_add_u64 v[140:141], s[22:23], 0, v[130:131]
	s_add_i32 m0, s24, 0x2000
	s_nop 0
	global_load_lds_dwordx4 v[140:141], off
	v_lshl_add_u64 v[140:141], v[188:189], 0, s[34:35]
	s_mov_b32 m0, s43
	s_nop 0
	global_load_lds_dwordx4 v[140:141], off
	v_lshl_add_u64 v[140:141], v[210:211], 0, s[34:35]
	s_mov_b32 m0, s44
	s_nop 0
	global_load_lds_dwordx4 v[140:141], off
	s_waitcnt vmcnt(8)
	s_waitcnt lgkmcnt(0)
	s_barrier
	s_setprio 1
	s_waitcnt lgkmcnt(0)
	v_mfma_f32_16x16x32_bf16 v[62:65], v[146:149], v[190:193], v[62:65]
	v_mfma_f32_16x16x32_bf16 v[62:65], v[150:153], v[194:197], v[62:65]
	v_mfma_f32_16x16x32_bf16 v[54:57], v[150:153], v[202:205], v[54:57]
	v_mfma_f32_16x16x32_bf16 v[54:57], v[146:149], v[198:201], v[54:57]
	v_mfma_f32_16x16x32_bf16 v[38:41], v[146:149], v[206:209], v[38:41]
	v_mfma_f32_16x16x32_bf16 v[38:41], v[150:153], v[228:231], v[38:41]
	v_mfma_f32_16x16x32_bf16 v[22:25], v[150:153], v[236:239], v[22:25]
	v_mfma_f32_16x16x32_bf16 v[22:25], v[146:149], v[232:235], v[22:25]
	v_mfma_f32_16x16x32_bf16 v[14:17], v[154:157], v[232:235], v[14:17]
	v_mfma_f32_16x16x32_bf16 v[14:17], v[158:161], v[236:239], v[14:17]
	v_mfma_f32_16x16x32_bf16 v[30:33], v[158:161], v[228:231], v[30:33]
	v_mfma_f32_16x16x32_bf16 v[30:33], v[154:157], v[206:209], v[30:33]
	v_mfma_f32_16x16x32_bf16 v[46:49], v[154:157], v[198:201], v[46:49]
	v_mfma_f32_16x16x32_bf16 v[46:49], v[158:161], v[202:205], v[46:49]
	v_mfma_f32_16x16x32_bf16 v[58:61], v[158:161], v[194:197], v[58:61]
	v_mfma_f32_16x16x32_bf16 v[58:61], v[154:157], v[190:193], v[58:61]
	s_setprio 0
	s_setprio 1
	v_mfma_f32_16x16x32_bf16 v[50:53], v[162:165], v[190:193], v[50:53]
	v_mfma_f32_16x16x32_bf16 v[50:53], v[166:169], v[194:197], v[50:53]
	v_mfma_f32_16x16x32_bf16 v[34:37], v[166:169], v[202:205], v[34:37]
	v_mfma_f32_16x16x32_bf16 v[34:37], v[162:165], v[198:201], v[34:37]
	v_mfma_f32_16x16x32_bf16 v[18:21], v[162:165], v[206:209], v[18:21]
	v_mfma_f32_16x16x32_bf16 v[18:21], v[166:169], v[228:231], v[18:21]
	v_mfma_f32_16x16x32_bf16 v[6:9], v[166:169], v[236:239], v[6:9]
	v_mfma_f32_16x16x32_bf16 v[6:9], v[162:165], v[232:235], v[6:9]
	v_mfma_f32_16x16x32_bf16 v[2:5], v[170:173], v[232:235], v[2:5]
	v_mfma_f32_16x16x32_bf16 v[2:5], v[178:181], v[236:239], v[2:5]
	v_mfma_f32_16x16x32_bf16 v[10:13], v[178:181], v[228:231], v[10:13]
	v_mfma_f32_16x16x32_bf16 v[10:13], v[170:173], v[206:209], v[10:13]
	v_mfma_f32_16x16x32_bf16 v[26:29], v[170:173], v[198:201], v[26:29]
	v_mfma_f32_16x16x32_bf16 v[26:29], v[178:181], v[202:205], v[26:29]
	v_mfma_f32_16x16x32_bf16 v[42:45], v[178:181], v[194:197], v[42:45]
	v_mfma_f32_16x16x32_bf16 v[42:45], v[170:173], v[190:193], v[42:45]
	s_add_i32 s52, s52, 2
	s_add_u32 s18, s18, 0x100
	s_addc_u32 s19, s19, 0
	s_add_u32 s50, s50, 0x100
	s_addc_u32 s51, s51, 0
	s_add_u32 s22, s18, 0xfff00080
	s_addc_u32 s23, s19, -1
	s_cmp_eq_u32 s52, 60
	s_cselect_b32 s25, s9, s23
	s_cselect_b32 s24, s48, s22
	s_cselect_b32 s23, s7, s51
	s_cselect_b32 s22, s49, s50
	s_cmp_gt_u32 s52, 61
	s_setprio 0
	s_barrier
	s_cbranch_scc0 .LBB0_575
	s_and_b64 vcc, exec, s[4:5]
	s_cbranch_vccz .LBB0_578
	s_barrier

.LBB0_720:
	s_ashr_i32 s7, s6, 31
	s_lshl_b64 s[8:9], s[6:7], 21
	s_add_u32 s8, s88, s8
	s_addc_u32 s9, s89, s9
	s_and_b64 s[14:15], s[38:39], exec
	s_cselect_b32 s7, s9, s17
	s_cselect_b32 s48, s8, s16
	s_ashr_i32 s5, s4, 31
	s_lshl_b64 s[14:15], s[4:5], 21
	s_add_u32 s14, s24, s14
	s_addc_u32 s15, s25, s15
	s_and_b64 s[22:23], s[38:39], exec
	s_cselect_b32 s5, s15, s19
	s_cselect_b32 s49, s14, s18
	s_add_u32 s16, s16, 0x100080
	s_addc_u32 s17, s17, 0
	s_add_u32 s50, s18, 0x100
	v_mov_b32_e32 v2, 0
	s_addc_u32 s51, s19, 0
	s_mov_b32 s52, -2
	v_mov_b32_e32 v3, v2
	v_mov_b32_e32 v4, v2
	v_mov_b32_e32 v5, v2
	v_mov_b32_e32 v10, v2
	v_mov_b32_e32 v11, v2
	v_mov_b32_e32 v12, v2
	v_mov_b32_e32 v13, v2
	v_mov_b32_e32 v18, v2
	v_mov_b32_e32 v19, v2
	v_mov_b32_e32 v20, v2
	v_mov_b32_e32 v21, v2
	v_mov_b32_e32 v26, v2
	v_mov_b32_e32 v27, v2
	v_mov_b32_e32 v28, v2
	v_mov_b32_e32 v29, v2
	v_mov_b32_e32 v34, v2
	v_mov_b32_e32 v35, v2
	v_mov_b32_e32 v36, v2
	v_mov_b32_e32 v37, v2
	v_mov_b32_e32 v42, v2
	v_mov_b32_e32 v43, v2
	v_mov_b32_e32 v44, v2
	v_mov_b32_e32 v45, v2
	v_mov_b32_e32 v50, v2
	v_mov_b32_e32 v51, v2
	v_mov_b32_e32 v52, v2
	v_mov_b32_e32 v53, v2
	v_mov_b32_e32 v58, v2
	v_mov_b32_e32 v59, v2
	v_mov_b32_e32 v60, v2
	v_mov_b32_e32 v61, v2
	v_mov_b32_e32 v6, v2
	v_mov_b32_e32 v7, v2
	v_mov_b32_e32 v8, v2
	v_mov_b32_e32 v9, v2
	v_mov_b32_e32 v14, v2
	v_mov_b32_e32 v15, v2
	v_mov_b32_e32 v16, v2
	v_mov_b32_e32 v17, v2
	v_mov_b32_e32 v22, v2
	v_mov_b32_e32 v23, v2
	v_mov_b32_e32 v24, v2
	v_mov_b32_e32 v25, v2
	v_mov_b32_e32 v30, v2
	v_mov_b32_e32 v31, v2
	v_mov_b32_e32 v32, v2
	v_mov_b32_e32 v33, v2
	v_mov_b32_e32 v38, v2
	v_mov_b32_e32 v39, v2
	v_mov_b32_e32 v40, v2
	v_mov_b32_e32 v41, v2
	v_mov_b32_e32 v46, v2
	v_mov_b32_e32 v47, v2
	v_mov_b32_e32 v48, v2
	v_mov_b32_e32 v49, v2
	v_mov_b32_e32 v54, v2
	v_mov_b32_e32 v55, v2
	v_mov_b32_e32 v56, v2
	v_mov_b32_e32 v57, v2
	v_mov_b32_e32 v62, v2
	v_mov_b32_e32 v63, v2
	v_mov_b32_e32 v64, v2
	v_mov_b32_e32 v65, v2
	v_mov_b32_e32 v66, v2
	v_mov_b32_e32 v67, v2
	v_mov_b32_e32 v68, v2
	v_mov_b32_e32 v69, v2
	v_mov_b32_e32 v74, v2
	v_mov_b32_e32 v75, v2
	v_mov_b32_e32 v76, v2
	v_mov_b32_e32 v77, v2
	v_mov_b32_e32 v82, v2
	v_mov_b32_e32 v83, v2
	v_mov_b32_e32 v84, v2
	v_mov_b32_e32 v85, v2
	v_mov_b32_e32 v90, v2
	v_mov_b32_e32 v91, v2
	v_mov_b32_e32 v92, v2
	v_mov_b32_e32 v93, v2
	v_mov_b32_e32 v98, v2
	v_mov_b32_e32 v99, v2
	v_mov_b32_e32 v100, v2
	v_mov_b32_e32 v101, v2
	v_mov_b32_e32 v106, v2
	v_mov_b32_e32 v107, v2
	v_mov_b32_e32 v108, v2
	v_mov_b32_e32 v109, v2
	v_mov_b32_e32 v114, v2
	v_mov_b32_e32 v115, v2
	v_mov_b32_e32 v116, v2
	v_mov_b32_e32 v117, v2
	v_mov_b32_e32 v122, v2
	v_mov_b32_e32 v123, v2
	v_mov_b32_e32 v124, v2
	v_mov_b32_e32 v125, v2
	v_mov_b32_e32 v70, v2
	v_mov_b32_e32 v71, v2
	v_mov_b32_e32 v72, v2
	v_mov_b32_e32 v73, v2
	v_mov_b32_e32 v78, v2
	v_mov_b32_e32 v79, v2
	v_mov_b32_e32 v80, v2
	v_mov_b32_e32 v81, v2
	v_mov_b32_e32 v86, v2
	v_mov_b32_e32 v87, v2
	v_mov_b32_e32 v88, v2
	v_mov_b32_e32 v89, v2
	v_mov_b32_e32 v94, v2
	v_mov_b32_e32 v95, v2
	v_mov_b32_e32 v96, v2
	v_mov_b32_e32 v97, v2
	v_mov_b32_e32 v102, v2
	v_mov_b32_e32 v103, v2
	v_mov_b32_e32 v104, v2
	v_mov_b32_e32 v105, v2
	v_mov_b32_e32 v110, v2
	v_mov_b32_e32 v111, v2
	v_mov_b32_e32 v112, v2
	v_mov_b32_e32 v113, v2
	v_mov_b32_e32 v118, v2
	v_mov_b32_e32 v119, v2
	v_mov_b32_e32 v120, v2
	v_mov_b32_e32 v121, v2
	v_mov_b32_e32 v126, v2
	v_mov_b32_e32 v127, v2
	v_mov_b32_e32 v128, v2
	v_mov_b32_e32 v129, v2
	s_add_u32 s18, s16, 0xfff00080
	s_addc_u32 s19, s17, -1
	s_cmp_eq_u32 s52, 60
	s_cselect_b32 s23, s7, s19
	s_cselect_b32 s22, s48, s18
	s_cselect_b32 s19, s5, s51
	s_cselect_b32 s18, s49, s50
.LBB0_721:
	s_add_i32 s53, 0, 0x10000
	v_add_u32_e32 v140, s53, v143
	s_add_i32 s56, 0, 0x14000
	ds_read_b128 v[146:149], v140
	ds_read_b128 v[150:153], v140 offset:1024
	ds_read_b128 v[154:157], v140 offset:2048
	ds_read_b128 v[158:161], v140 offset:3072
	v_add_u32_e32 v140, s56, v143
	ds_read_b128 v[162:165], v140
	ds_read_b128 v[166:169], v140 offset:1024
	ds_read_b128 v[170:173], v140 offset:2048
	ds_read_b128 v[178:181], v140 offset:3072
	v_lshl_add_u64 v[140:141], s[16:17], 0, v[136:137]
	s_add_i32 m0, s31, 0xc000
	ds_read_b128 v[190:193], v145
	ds_read_b128 v[194:197], v145 offset:1024
	ds_read_b128 v[198:201], v145 offset:2048
	ds_read_b128 v[202:205], v145 offset:3072
	ds_read_b128 v[206:209], v145 offset:4096
	ds_read_b128 v[228:231], v145 offset:5120
	ds_read_b128 v[232:235], v145 offset:6144
	ds_read_b128 v[236:239], v145 offset:7168
	global_load_lds_dwordx4 v[140:141], off
	v_lshl_add_u64 v[140:141], s[16:17], 0, v[138:139]
	s_add_i32 m0, s31, 0xe000
	s_nop 0
	global_load_lds_dwordx4 v[140:141], off
	s_waitcnt vmcnt(8)
	s_waitcnt lgkmcnt(0)
	s_barrier
	s_setprio 1
	s_waitcnt lgkmcnt(0)
	v_mfma_f32_16x16x32_bf16 v[126:129], v[146:149], v[190:193], v[126:129]
	v_mfma_f32_16x16x32_bf16 v[126:129], v[150:153], v[194:197], v[126:129]
	v_mfma_f32_16x16x32_bf16 v[110:113], v[150:153], v[202:205], v[110:113]
	v_mfma_f32_16x16x32_bf16 v[110:113], v[146:149], v[198:201], v[110:113]
	v_mfma_f32_16x16x32_bf16 v[94:97], v[146:149], v[206:209], v[94:97]
	v_mfma_f32_16x16x32_bf16 v[94:97], v[150:153], v[228:231], v[94:97]
	v_mfma_f32_16x16x32_bf16 v[78:81], v[150:153], v[236:239], v[78:81]
	v_mfma_f32_16x16x32_bf16 v[78:81], v[146:149], v[232:235], v[78:81]
	v_mfma_f32_16x16x32_bf16 v[70:73], v[154:157], v[232:235], v[70:73]
	v_mfma_f32_16x16x32_bf16 v[70:73], v[158:161], v[236:239], v[70:73]
	v_mfma_f32_16x16x32_bf16 v[86:89], v[158:161], v[228:231], v[86:89]
	v_mfma_f32_16x16x32_bf16 v[86:89], v[154:157], v[206:209], v[86:89]
	v_mfma_f32_16x16x32_bf16 v[102:105], v[154:157], v[198:201], v[102:105]
	v_mfma_f32_16x16x32_bf16 v[102:105], v[158:161], v[202:205], v[102:105]
	v_mfma_f32_16x16x32_bf16 v[118:121], v[158:161], v[194:197], v[118:121]
	v_mfma_f32_16x16x32_bf16 v[118:121], v[154:157], v[190:193], v[118:121]
	s_setprio 0
	s_setprio 1
	v_mfma_f32_16x16x32_bf16 v[122:125], v[162:165], v[190:193], v[122:125]
	v_mfma_f32_16x16x32_bf16 v[122:125], v[166:169], v[194:197], v[122:125]
	v_mfma_f32_16x16x32_bf16 v[106:109], v[166:169], v[202:205], v[106:109]
	v_mfma_f32_16x16x32_bf16 v[106:109], v[162:165], v[198:201], v[106:109]
	v_mfma_f32_16x16x32_bf16 v[90:93], v[162:165], v[206:209], v[90:93]
	v_mfma_f32_16x16x32_bf16 v[90:93], v[166:169], v[228:231], v[90:93]
	v_mfma_f32_16x16x32_bf16 v[74:77], v[166:169], v[236:239], v[74:77]
	v_mfma_f32_16x16x32_bf16 v[74:77], v[162:165], v[232:235], v[74:77]
	v_mfma_f32_16x16x32_bf16 v[66:69], v[170:173], v[232:235], v[66:69]
	v_mfma_f32_16x16x32_bf16 v[66:69], v[178:181], v[236:239], v[66:69]
	v_mfma_f32_16x16x32_bf16 v[82:85], v[178:181], v[228:231], v[82:85]
	v_mfma_f32_16x16x32_bf16 v[82:85], v[170:173], v[206:209], v[82:85]
	v_mfma_f32_16x16x32_bf16 v[98:101], v[170:173], v[198:201], v[98:101]
	v_mfma_f32_16x16x32_bf16 v[98:101], v[178:181], v[202:205], v[98:101]
	v_mfma_f32_16x16x32_bf16 v[114:117], v[178:181], v[194:197], v[114:117]
	v_mfma_f32_16x16x32_bf16 v[114:117], v[170:173], v[190:193], v[114:117]
	s_setprio 0
	s_barrier
	s_add_i32 s53, s53, s26
	v_lshl_add_u64 v[140:141], s[18:19], 0, v[0:1]
	s_mov_b32 m0, s53
	ds_read_b128 v[190:193], v145 offset:16384
	ds_read_b128 v[194:197], v145 offset:17408
	ds_read_b128 v[198:201], v145 offset:18432
	ds_read_b128 v[202:205], v145 offset:19456
	ds_read_b128 v[206:209], v145 offset:20480
	ds_read_b128 v[228:231], v145 offset:21504
	ds_read_b128 v[232:235], v145 offset:22528
	ds_read_b128 v[236:239], v145 offset:23552
	global_load_lds_dwordx4 v[140:141], off
	s_add_i32 m0, s53, 0x2000
	s_add_u32 s54, s18, 0x100000
	v_lshl_add_u64 v[186:187], s[18:19], 0, v[130:131]
	s_addc_u32 s55, s19, 0
	s_add_i32 s53, s56, s26
	global_load_lds_dwordx4 v[186:187], off
	v_lshl_add_u64 v[188:189], s[54:55], 0, v[0:1]
	s_mov_b32 m0, s53
	v_lshl_add_u64 v[210:211], s[22:23], 0, v[132:133]
	global_load_lds_dwordx4 v[188:189], off
	v_lshl_add_u64 v[188:189], s[54:55], 0, v[130:131]
	s_add_i32 m0, s53, 0x2000
	s_nop 0
	global_load_lds_dwordx4 v[188:189], off
	v_lshl_add_u64 v[188:189], s[22:23], 0, v[134:135]
	s_mov_b32 m0, s31
	s_nop 0
	global_load_lds_dwordx4 v[188:189], off
	s_mov_b32 m0, s40
	s_nop 0
	global_load_lds_dwordx4 v[210:211], off
	s_waitcnt vmcnt(8)
	s_waitcnt lgkmcnt(0)
	s_barrier
	s_setprio 1
	s_waitcnt lgkmcnt(0)
	v_mfma_f32_16x16x32_bf16 v[62:65], v[146:149], v[190:193], v[62:65]
	v_mfma_f32_16x16x32_bf16 v[62:65], v[150:153], v[194:197], v[62:65]
	v_mfma_f32_16x16x32_bf16 v[46:49], v[150:153], v[202:205], v[46:49]
	v_mfma_f32_16x16x32_bf16 v[46:49], v[146:149], v[198:201], v[46:49]
	v_mfma_f32_16x16x32_bf16 v[30:33], v[146:149], v[206:209], v[30:33]
	v_mfma_f32_16x16x32_bf16 v[30:33], v[150:153], v[228:231], v[30:33]
	v_mfma_f32_16x16x32_bf16 v[14:17], v[150:153], v[236:239], v[14:17]
	v_mfma_f32_16x16x32_bf16 v[14:17], v[146:149], v[232:235], v[14:17]
	v_mfma_f32_16x16x32_bf16 v[6:9], v[154:157], v[232:235], v[6:9]
	v_mfma_f32_16x16x32_bf16 v[6:9], v[158:161], v[236:239], v[6:9]
	v_mfma_f32_16x16x32_bf16 v[22:25], v[158:161], v[228:231], v[22:25]
	v_mfma_f32_16x16x32_bf16 v[22:25], v[154:157], v[206:209], v[22:25]
	v_mfma_f32_16x16x32_bf16 v[38:41], v[154:157], v[198:201], v[38:41]
	v_mfma_f32_16x16x32_bf16 v[38:41], v[158:161], v[202:205], v[38:41]
	v_mfma_f32_16x16x32_bf16 v[54:57], v[158:161], v[194:197], v[54:57]
	v_mfma_f32_16x16x32_bf16 v[54:57], v[154:157], v[190:193], v[54:57]
	s_setprio 0
	s_setprio 1
	v_mfma_f32_16x16x32_bf16 v[58:61], v[162:165], v[190:193], v[58:61]
	v_mfma_f32_16x16x32_bf16 v[58:61], v[166:169], v[194:197], v[58:61]
	v_mfma_f32_16x16x32_bf16 v[42:45], v[166:169], v[202:205], v[42:45]
	v_mfma_f32_16x16x32_bf16 v[42:45], v[162:165], v[198:201], v[42:45]
	v_mfma_f32_16x16x32_bf16 v[26:29], v[162:165], v[206:209], v[26:29]
	v_mfma_f32_16x16x32_bf16 v[26:29], v[166:169], v[228:231], v[26:29]
	v_mfma_f32_16x16x32_bf16 v[10:13], v[166:169], v[236:239], v[10:13]
	v_mfma_f32_16x16x32_bf16 v[10:13], v[162:165], v[232:235], v[10:13]
	v_mfma_f32_16x16x32_bf16 v[2:5], v[170:173], v[232:235], v[2:5]
	v_mfma_f32_16x16x32_bf16 v[2:5], v[178:181], v[236:239], v[2:5]
	v_mfma_f32_16x16x32_bf16 v[18:21], v[178:181], v[228:231], v[18:21]
	v_mfma_f32_16x16x32_bf16 v[18:21], v[170:173], v[206:209], v[18:21]
	v_mfma_f32_16x16x32_bf16 v[34:37], v[170:173], v[198:201], v[34:37]
	v_mfma_f32_16x16x32_bf16 v[34:37], v[178:181], v[202:205], v[34:37]
	v_mfma_f32_16x16x32_bf16 v[50:53], v[178:181], v[194:197], v[50:53]
	v_mfma_f32_16x16x32_bf16 v[50:53], v[170:173], v[190:193], v[50:53]
	s_setprio 0
	s_barrier
	s_add_i32 s53, 0, 0x18000
	s_add_i32 s54, 0, 0x1c000
	v_add_u32_e32 v158, s53, v143
	v_add_u32_e32 v175, s54, v143
	ds_read_b128 v[146:149], v158
	ds_read_b128 v[150:153], v158 offset:1024
	ds_read_b128 v[154:157], v158 offset:2048
	ds_read_b128 v[158:161], v158 offset:3072
	ds_read_b128 v[162:165], v175
	ds_read_b128 v[166:169], v175 offset:1024
	ds_read_b128 v[170:173], v175 offset:2048
	ds_read_b128 v[178:181], v175 offset:3072
	s_add_u32 s22, s22, 0x100000
	s_addc_u32 s23, s23, 0
	s_mov_b32 m0, s41
	v_lshl_add_u64 v[226:227], s[22:23], 0, v[134:135]
	ds_read_b128 v[190:193], v145 offset:32768
	ds_read_b128 v[194:197], v145 offset:33792
	ds_read_b128 v[198:201], v145 offset:34816
	ds_read_b128 v[202:205], v145 offset:35840
	ds_read_b128 v[206:209], v145 offset:36864
	ds_read_b128 v[228:231], v145 offset:37888
	ds_read_b128 v[232:235], v145 offset:38912
	ds_read_b128 v[236:239], v145 offset:39936
	global_load_lds_dwordx4 v[226:227], off
	v_lshl_add_u64 v[226:227], s[22:23], 0, v[132:133]
	s_mov_b32 m0, s42
	s_nop 0
	global_load_lds_dwordx4 v[226:227], off
	s_waitcnt vmcnt(8)
	s_waitcnt lgkmcnt(0)
	s_barrier
	s_setprio 1
	s_waitcnt lgkmcnt(0)
	v_mfma_f32_16x16x32_bf16 v[126:129], v[146:149], v[190:193], v[126:129]
	v_mfma_f32_16x16x32_bf16 v[126:129], v[150:153], v[194:197], v[126:129]
	v_mfma_f32_16x16x32_bf16 v[110:113], v[150:153], v[202:205], v[110:113]
	v_mfma_f32_16x16x32_bf16 v[110:113], v[146:149], v[198:201], v[110:113]
	v_mfma_f32_16x16x32_bf16 v[94:97], v[146:149], v[206:209], v[94:97]
	v_mfma_f32_16x16x32_bf16 v[94:97], v[150:153], v[228:231], v[94:97]
	v_mfma_f32_16x16x32_bf16 v[78:81], v[150:153], v[236:239], v[78:81]
	v_mfma_f32_16x16x32_bf16 v[78:81], v[146:149], v[232:235], v[78:81]
	v_mfma_f32_16x16x32_bf16 v[70:73], v[154:157], v[232:235], v[70:73]
	v_mfma_f32_16x16x32_bf16 v[70:73], v[158:161], v[236:239], v[70:73]
	v_mfma_f32_16x16x32_bf16 v[86:89], v[158:161], v[228:231], v[86:89]
	v_mfma_f32_16x16x32_bf16 v[86:89], v[154:157], v[206:209], v[86:89]
	v_mfma_f32_16x16x32_bf16 v[102:105], v[154:157], v[198:201], v[102:105]
	v_mfma_f32_16x16x32_bf16 v[102:105], v[158:161], v[202:205], v[102:105]
	v_mfma_f32_16x16x32_bf16 v[118:121], v[158:161], v[194:197], v[118:121]
	v_mfma_f32_16x16x32_bf16 v[118:121], v[154:157], v[190:193], v[118:121]
	s_setprio 0
	s_setprio 1
	v_mfma_f32_16x16x32_bf16 v[122:125], v[162:165], v[190:193], v[122:125]
	v_mfma_f32_16x16x32_bf16 v[122:125], v[166:169], v[194:197], v[122:125]
	v_mfma_f32_16x16x32_bf16 v[106:109], v[166:169], v[202:205], v[106:109]
	v_mfma_f32_16x16x32_bf16 v[106:109], v[162:165], v[198:201], v[106:109]
	v_mfma_f32_16x16x32_bf16 v[90:93], v[162:165], v[206:209], v[90:93]
	v_mfma_f32_16x16x32_bf16 v[90:93], v[166:169], v[228:231], v[90:93]
	v_mfma_f32_16x16x32_bf16 v[74:77], v[166:169], v[236:239], v[74:77]
	v_mfma_f32_16x16x32_bf16 v[74:77], v[162:165], v[232:235], v[74:77]
	v_mfma_f32_16x16x32_bf16 v[66:69], v[170:173], v[232:235], v[66:69]
	v_mfma_f32_16x16x32_bf16 v[66:69], v[178:181], v[236:239], v[66:69]
	v_mfma_f32_16x16x32_bf16 v[82:85], v[178:181], v[228:231], v[82:85]
	v_mfma_f32_16x16x32_bf16 v[82:85], v[170:173], v[206:209], v[82:85]
	v_mfma_f32_16x16x32_bf16 v[98:101], v[170:173], v[198:201], v[98:101]
	v_mfma_f32_16x16x32_bf16 v[98:101], v[178:181], v[202:205], v[98:101]
	v_mfma_f32_16x16x32_bf16 v[114:117], v[178:181], v[194:197], v[114:117]
	v_mfma_f32_16x16x32_bf16 v[114:117], v[170:173], v[190:193], v[114:117]
	s_setprio 0
	s_barrier
	s_add_i32 s22, s53, s26
	v_lshl_add_u64 v[140:141], v[140:141], 0, s[34:35]
	s_mov_b32 m0, s22
	ds_read_b128 v[190:193], v145 offset:49152
	ds_read_b128 v[194:197], v145 offset:50176
	ds_read_b128 v[198:201], v145 offset:51200
	ds_read_b128 v[202:205], v145 offset:52224
	ds_read_b128 v[206:209], v145 offset:53248
	ds_read_b128 v[228:231], v145 offset:54272
	ds_read_b128 v[232:235], v145 offset:55296
	ds_read_b128 v[236:239], v145 offset:56320
	global_load_lds_dwordx4 v[140:141], off
	s_add_i32 m0, s22, 0x2000
	s_add_u32 s18, s18, 0x100080
	v_lshl_add_u64 v[140:141], v[186:187], 0, s[34:35]
	s_addc_u32 s19, s19, 0
	s_add_i32 s22, s54, s26
	global_load_lds_dwordx4 v[140:141], off
	v_lshl_add_u64 v[140:141], s[18:19], 0, v[0:1]
	s_mov_b32 m0, s22
	s_nop 0
	global_load_lds_dwordx4 v[140:141], off
	v_lshl_add_u64 v[140:141], s[18:19], 0, v[130:131]
	s_add_i32 m0, s22, 0x2000
	s_nop 0
	global_load_lds_dwordx4 v[140:141], off
	v_lshl_add_u64 v[140:141], v[188:189], 0, s[34:35]
	s_mov_b32 m0, s43
	s_nop 0
	global_load_lds_dwordx4 v[140:141], off
	v_lshl_add_u64 v[140:141], v[210:211], 0, s[34:35]
	s_mov_b32 m0, s44
	s_nop 0
	global_load_lds_dwordx4 v[140:141], off
	s_waitcnt vmcnt(8)
	s_waitcnt lgkmcnt(0)
	s_barrier
	s_setprio 1
	s_waitcnt lgkmcnt(0)
	v_mfma_f32_16x16x32_bf16 v[62:65], v[146:149], v[190:193], v[62:65]
	v_mfma_f32_16x16x32_bf16 v[62:65], v[150:153], v[194:197], v[62:65]
	v_mfma_f32_16x16x32_bf16 v[46:49], v[150:153], v[202:205], v[46:49]
	v_mfma_f32_16x16x32_bf16 v[46:49], v[146:149], v[198:201], v[46:49]
	v_mfma_f32_16x16x32_bf16 v[30:33], v[146:149], v[206:209], v[30:33]
	v_mfma_f32_16x16x32_bf16 v[30:33], v[150:153], v[228:231], v[30:33]
	v_mfma_f32_16x16x32_bf16 v[14:17], v[150:153], v[236:239], v[14:17]
	v_mfma_f32_16x16x32_bf16 v[14:17], v[146:149], v[232:235], v[14:17]
	v_mfma_f32_16x16x32_bf16 v[6:9], v[154:157], v[232:235], v[6:9]
	v_mfma_f32_16x16x32_bf16 v[6:9], v[158:161], v[236:239], v[6:9]
	v_mfma_f32_16x16x32_bf16 v[22:25], v[158:161], v[228:231], v[22:25]
	v_mfma_f32_16x16x32_bf16 v[22:25], v[154:157], v[206:209], v[22:25]
	v_mfma_f32_16x16x32_bf16 v[38:41], v[154:157], v[198:201], v[38:41]
	v_mfma_f32_16x16x32_bf16 v[38:41], v[158:161], v[202:205], v[38:41]
	v_mfma_f32_16x16x32_bf16 v[54:57], v[158:161], v[194:197], v[54:57]
	v_mfma_f32_16x16x32_bf16 v[54:57], v[154:157], v[190:193], v[54:57]
	s_setprio 0
	s_setprio 1
	v_mfma_f32_16x16x32_bf16 v[58:61], v[162:165], v[190:193], v[58:61]
	v_mfma_f32_16x16x32_bf16 v[58:61], v[166:169], v[194:197], v[58:61]
	v_mfma_f32_16x16x32_bf16 v[42:45], v[166:169], v[202:205], v[42:45]
	v_mfma_f32_16x16x32_bf16 v[42:45], v[162:165], v[198:201], v[42:45]
	v_mfma_f32_16x16x32_bf16 v[26:29], v[162:165], v[206:209], v[26:29]
	v_mfma_f32_16x16x32_bf16 v[26:29], v[166:169], v[228:231], v[26:29]
	v_mfma_f32_16x16x32_bf16 v[10:13], v[166:169], v[236:239], v[10:13]
	v_mfma_f32_16x16x32_bf16 v[10:13], v[162:165], v[232:235], v[10:13]
	v_mfma_f32_16x16x32_bf16 v[2:5], v[170:173], v[232:235], v[2:5]
	v_mfma_f32_16x16x32_bf16 v[2:5], v[178:181], v[236:239], v[2:5]
	v_mfma_f32_16x16x32_bf16 v[18:21], v[178:181], v[228:231], v[18:21]
	v_mfma_f32_16x16x32_bf16 v[18:21], v[170:173], v[206:209], v[18:21]
	v_mfma_f32_16x16x32_bf16 v[34:37], v[170:173], v[198:201], v[34:37]
	v_mfma_f32_16x16x32_bf16 v[34:37], v[178:181], v[202:205], v[34:37]
	v_mfma_f32_16x16x32_bf16 v[50:53], v[178:181], v[194:197], v[50:53]
	v_mfma_f32_16x16x32_bf16 v[50:53], v[170:173], v[190:193], v[50:53]
	s_add_i32 s52, s52, 2
	s_add_u32 s16, s16, 0x100
	s_addc_u32 s17, s17, 0
	s_add_u32 s50, s50, 0x100
	s_addc_u32 s51, s51, 0
	s_add_u32 s18, s16, 0xfff00080
	s_addc_u32 s19, s17, -1
	s_cmp_eq_u32 s52, 60
	s_cselect_b32 s23, s7, s19
	s_cselect_b32 s22, s48, s18
	s_cselect_b32 s19, s5, s51
	s_cselect_b32 s18, s49, s50
	s_cmp_gt_u32 s52, 61
	s_setprio 0
	s_barrier
	s_cbranch_scc0 .LBB0_721
	s_and_b64 vcc, exec, s[2:3]
	s_cbranch_vccz .LBB0_724
	s_barrier

.LBB0_804:
	s_add_u32 s46, s16, 0x100
	v_mov_b32_e32 v2, 0
	s_addc_u32 s47, s17, 0
	s_mov_b32 s48, -2
	v_mov_b32_e32 v3, v2
	v_mov_b32_e32 v4, v2
	v_mov_b32_e32 v5, v2
	v_mov_b32_e32 v6, v2
	v_mov_b32_e32 v7, v2
	v_mov_b32_e32 v8, v2
	v_mov_b32_e32 v9, v2
	v_mov_b32_e32 v10, v2
	v_mov_b32_e32 v11, v2
	v_mov_b32_e32 v12, v2
	v_mov_b32_e32 v13, v2
	v_mov_b32_e32 v18, v2
	v_mov_b32_e32 v19, v2
	v_mov_b32_e32 v20, v2
	v_mov_b32_e32 v21, v2
	v_mov_b32_e32 v26, v2
	v_mov_b32_e32 v27, v2
	v_mov_b32_e32 v28, v2
	v_mov_b32_e32 v29, v2
	v_mov_b32_e32 v34, v2
	v_mov_b32_e32 v35, v2
	v_mov_b32_e32 v36, v2
	v_mov_b32_e32 v37, v2
	v_mov_b32_e32 v42, v2
	v_mov_b32_e32 v43, v2
	v_mov_b32_e32 v44, v2
	v_mov_b32_e32 v45, v2
	v_mov_b32_e32 v50, v2
	v_mov_b32_e32 v51, v2
	v_mov_b32_e32 v52, v2
	v_mov_b32_e32 v53, v2
	v_mov_b32_e32 v14, v2
	v_mov_b32_e32 v15, v2
	v_mov_b32_e32 v16, v2
	v_mov_b32_e32 v17, v2
	v_mov_b32_e32 v22, v2
	v_mov_b32_e32 v23, v2
	v_mov_b32_e32 v24, v2
	v_mov_b32_e32 v25, v2
	v_mov_b32_e32 v30, v2
	v_mov_b32_e32 v31, v2
	v_mov_b32_e32 v32, v2
	v_mov_b32_e32 v33, v2
	v_mov_b32_e32 v38, v2
	v_mov_b32_e32 v39, v2
	v_mov_b32_e32 v40, v2
	v_mov_b32_e32 v41, v2
	v_mov_b32_e32 v46, v2
	v_mov_b32_e32 v47, v2
	v_mov_b32_e32 v48, v2
	v_mov_b32_e32 v49, v2
	v_mov_b32_e32 v54, v2
	v_mov_b32_e32 v55, v2
	v_mov_b32_e32 v56, v2
	v_mov_b32_e32 v57, v2
	v_mov_b32_e32 v58, v2
	v_mov_b32_e32 v59, v2
	v_mov_b32_e32 v60, v2
	v_mov_b32_e32 v61, v2
	v_mov_b32_e32 v62, v2
	v_mov_b32_e32 v63, v2
	v_mov_b32_e32 v64, v2
	v_mov_b32_e32 v65, v2
	v_mov_b32_e32 v66, v2
	v_mov_b32_e32 v67, v2
	v_mov_b32_e32 v68, v2
	v_mov_b32_e32 v69, v2
	v_mov_b32_e32 v70, v2
	v_mov_b32_e32 v71, v2
	v_mov_b32_e32 v72, v2
	v_mov_b32_e32 v73, v2
	v_mov_b32_e32 v74, v2
	v_mov_b32_e32 v75, v2
	v_mov_b32_e32 v76, v2
	v_mov_b32_e32 v77, v2
	v_mov_b32_e32 v82, v2
	v_mov_b32_e32 v83, v2
	v_mov_b32_e32 v84, v2
	v_mov_b32_e32 v85, v2
	v_mov_b32_e32 v90, v2
	v_mov_b32_e32 v91, v2
	v_mov_b32_e32 v92, v2
	v_mov_b32_e32 v93, v2
	v_mov_b32_e32 v98, v2
	v_mov_b32_e32 v99, v2
	v_mov_b32_e32 v100, v2
	v_mov_b32_e32 v101, v2
	v_mov_b32_e32 v106, v2
	v_mov_b32_e32 v107, v2
	v_mov_b32_e32 v108, v2
	v_mov_b32_e32 v109, v2
	v_mov_b32_e32 v114, v2
	v_mov_b32_e32 v115, v2
	v_mov_b32_e32 v116, v2
	v_mov_b32_e32 v117, v2
	v_mov_b32_e32 v78, v2
	v_mov_b32_e32 v79, v2
	v_mov_b32_e32 v80, v2
	v_mov_b32_e32 v81, v2
	v_mov_b32_e32 v86, v2
	v_mov_b32_e32 v87, v2
	v_mov_b32_e32 v88, v2
	v_mov_b32_e32 v89, v2
	v_mov_b32_e32 v94, v2
	v_mov_b32_e32 v95, v2
	v_mov_b32_e32 v96, v2
	v_mov_b32_e32 v97, v2
	v_mov_b32_e32 v102, v2
	v_mov_b32_e32 v103, v2
	v_mov_b32_e32 v104, v2
	v_mov_b32_e32 v105, v2
	v_mov_b32_e32 v110, v2
	v_mov_b32_e32 v111, v2
	v_mov_b32_e32 v112, v2
	v_mov_b32_e32 v113, v2
	v_mov_b32_e32 v118, v2
	v_mov_b32_e32 v119, v2
	v_mov_b32_e32 v120, v2
	v_mov_b32_e32 v121, v2
	v_mov_b32_e32 v122, v2
	v_mov_b32_e32 v123, v2
	v_mov_b32_e32 v124, v2
	v_mov_b32_e32 v125, v2
	v_mov_b32_e32 v126, v2
	v_mov_b32_e32 v127, v2
	v_mov_b32_e32 v128, v2
	v_mov_b32_e32 v129, v2
	s_add_u32 s16, s14, 0x100
	s_addc_u32 s17, s15, 0
	s_cmpk_eq_i32 s48, 0xa8
	s_cselect_b32 s23, s5, s17
	s_cselect_b32 s22, s4, s16
	s_cselect_b32 s19, s9, s47
	s_cselect_b32 s18, s8, s46
.LBB0_805:
	s_add_i32 s49, 0, 0x10000
	v_add_u32_e32 v140, s49, v143
	s_add_i32 s50, 0, 0x14000
	ds_read_b128 v[146:149], v140
	ds_read_b128 v[150:153], v140 offset:1024
	ds_read_b128 v[154:157], v140 offset:2048
	ds_read_b128 v[158:161], v140 offset:3072
	v_add_u32_e32 v140, s50, v143
	ds_read_b128 v[162:165], v140
	ds_read_b128 v[166:169], v140 offset:1024
	ds_read_b128 v[170:173], v140 offset:2048
	ds_read_b128 v[178:181], v140 offset:3072
	v_lshl_add_u64 v[140:141], s[14:15], 0, v[136:137]
	s_add_i32 m0, s31, 0xc000
	ds_read_b128 v[190:193], v145
	ds_read_b128 v[194:197], v145 offset:1024
	ds_read_b128 v[198:201], v145 offset:2048
	ds_read_b128 v[202:205], v145 offset:3072
	ds_read_b128 v[206:209], v145 offset:4096
	ds_read_b128 v[228:231], v145 offset:5120
	ds_read_b128 v[232:235], v145 offset:6144
	ds_read_b128 v[236:239], v145 offset:7168
	global_load_lds_dwordx4 v[140:141], off
	v_lshl_add_u64 v[140:141], s[14:15], 0, v[138:139]
	s_add_i32 m0, s31, 0xe000
	s_nop 0
	global_load_lds_dwordx4 v[140:141], off
	s_waitcnt vmcnt(8)
	s_waitcnt lgkmcnt(0)
	s_barrier
	s_setprio 1
	s_waitcnt lgkmcnt(0)
	v_mfma_f32_16x16x32_bf16 v[126:129], v[146:149], v[190:193], v[126:129]
	v_mfma_f32_16x16x32_bf16 v[126:129], v[150:153], v[194:197], v[126:129]
	v_mfma_f32_16x16x32_bf16 v[118:121], v[150:153], v[202:205], v[118:121]
	v_mfma_f32_16x16x32_bf16 v[118:121], v[146:149], v[198:201], v[118:121]
	v_mfma_f32_16x16x32_bf16 v[102:105], v[146:149], v[206:209], v[102:105]
	v_mfma_f32_16x16x32_bf16 v[102:105], v[150:153], v[228:231], v[102:105]
	v_mfma_f32_16x16x32_bf16 v[86:89], v[150:153], v[236:239], v[86:89]
	v_mfma_f32_16x16x32_bf16 v[86:89], v[146:149], v[232:235], v[86:89]
	v_mfma_f32_16x16x32_bf16 v[78:81], v[154:157], v[232:235], v[78:81]
	v_mfma_f32_16x16x32_bf16 v[78:81], v[158:161], v[236:239], v[78:81]
	v_mfma_f32_16x16x32_bf16 v[94:97], v[158:161], v[228:231], v[94:97]
	v_mfma_f32_16x16x32_bf16 v[94:97], v[154:157], v[206:209], v[94:97]
	v_mfma_f32_16x16x32_bf16 v[110:113], v[154:157], v[198:201], v[110:113]
	v_mfma_f32_16x16x32_bf16 v[110:113], v[158:161], v[202:205], v[110:113]
	v_mfma_f32_16x16x32_bf16 v[122:125], v[158:161], v[194:197], v[122:125]
	v_mfma_f32_16x16x32_bf16 v[122:125], v[154:157], v[190:193], v[122:125]
	s_setprio 0
	s_setprio 1
	v_mfma_f32_16x16x32_bf16 v[114:117], v[162:165], v[190:193], v[114:117]
	v_mfma_f32_16x16x32_bf16 v[114:117], v[166:169], v[194:197], v[114:117]
	v_mfma_f32_16x16x32_bf16 v[98:101], v[166:169], v[202:205], v[98:101]
	v_mfma_f32_16x16x32_bf16 v[98:101], v[162:165], v[198:201], v[98:101]
	v_mfma_f32_16x16x32_bf16 v[82:85], v[162:165], v[206:209], v[82:85]
	v_mfma_f32_16x16x32_bf16 v[82:85], v[166:169], v[228:231], v[82:85]
	v_mfma_f32_16x16x32_bf16 v[70:73], v[166:169], v[236:239], v[70:73]
	v_mfma_f32_16x16x32_bf16 v[70:73], v[162:165], v[232:235], v[70:73]
	v_mfma_f32_16x16x32_bf16 v[66:69], v[170:173], v[232:235], v[66:69]
	v_mfma_f32_16x16x32_bf16 v[66:69], v[178:181], v[236:239], v[66:69]
	v_mfma_f32_16x16x32_bf16 v[74:77], v[178:181], v[228:231], v[74:77]
	v_mfma_f32_16x16x32_bf16 v[74:77], v[170:173], v[206:209], v[74:77]
	v_mfma_f32_16x16x32_bf16 v[90:93], v[170:173], v[198:201], v[90:93]
	v_mfma_f32_16x16x32_bf16 v[90:93], v[178:181], v[202:205], v[90:93]
	v_mfma_f32_16x16x32_bf16 v[106:109], v[178:181], v[194:197], v[106:109]
	v_mfma_f32_16x16x32_bf16 v[106:109], v[170:173], v[190:193], v[106:109]
	s_setprio 0
	s_barrier
	s_add_i32 s14, s49, s26
	v_lshl_add_u64 v[140:141], s[18:19], 0, v[0:1]
	s_mov_b32 m0, s14
	ds_read_b128 v[190:193], v145 offset:16384
	ds_read_b128 v[194:197], v145 offset:17408
	ds_read_b128 v[198:201], v145 offset:18432
	ds_read_b128 v[202:205], v145 offset:19456
	ds_read_b128 v[206:209], v145 offset:20480
	ds_read_b128 v[228:231], v145 offset:21504
	ds_read_b128 v[232:235], v145 offset:22528
	ds_read_b128 v[236:239], v145 offset:23552
	global_load_lds_dwordx4 v[140:141], off
	s_add_i32 m0, s14, 0x2000
	s_add_u32 s14, s18, 0x2b0000
	v_lshl_add_u64 v[186:187], s[18:19], 0, v[130:131]
	s_addc_u32 s15, s19, 0
	s_add_i32 s49, s50, s26
	global_load_lds_dwordx4 v[186:187], off
	v_lshl_add_u64 v[188:189], s[14:15], 0, v[0:1]
	s_mov_b32 m0, s49
	v_lshl_add_u64 v[210:211], s[22:23], 0, v[132:133]
	global_load_lds_dwordx4 v[188:189], off
	v_lshl_add_u64 v[188:189], s[14:15], 0, v[130:131]
	s_add_i32 m0, s49, 0x2000
	s_nop 0
	global_load_lds_dwordx4 v[188:189], off
	v_lshl_add_u64 v[188:189], s[22:23], 0, v[134:135]
	s_mov_b32 m0, s31
	s_nop 0
	global_load_lds_dwordx4 v[188:189], off
	s_mov_b32 m0, s36
	s_nop 0
	global_load_lds_dwordx4 v[210:211], off
	s_waitcnt vmcnt(8)
	s_waitcnt lgkmcnt(0)
	s_barrier
	s_setprio 1
	s_waitcnt lgkmcnt(0)
	v_mfma_f32_16x16x32_bf16 v[62:65], v[146:149], v[190:193], v[62:65]
	v_mfma_f32_16x16x32_bf16 v[62:65], v[150:153], v[194:197], v[62:65]
	v_mfma_f32_16x16x32_bf16 v[54:57], v[150:153], v[202:205], v[54:57]
	v_mfma_f32_16x16x32_bf16 v[54:57], v[146:149], v[198:201], v[54:57]
	v_mfma_f32_16x16x32_bf16 v[38:41], v[146:149], v[206:209], v[38:41]
	v_mfma_f32_16x16x32_bf16 v[38:41], v[150:153], v[228:231], v[38:41]
	v_mfma_f32_16x16x32_bf16 v[22:25], v[150:153], v[236:239], v[22:25]
	v_mfma_f32_16x16x32_bf16 v[22:25], v[146:149], v[232:235], v[22:25]
	v_mfma_f32_16x16x32_bf16 v[14:17], v[154:157], v[232:235], v[14:17]
	v_mfma_f32_16x16x32_bf16 v[14:17], v[158:161], v[236:239], v[14:17]
	v_mfma_f32_16x16x32_bf16 v[30:33], v[158:161], v[228:231], v[30:33]
	v_mfma_f32_16x16x32_bf16 v[30:33], v[154:157], v[206:209], v[30:33]
	v_mfma_f32_16x16x32_bf16 v[46:49], v[154:157], v[198:201], v[46:49]
	v_mfma_f32_16x16x32_bf16 v[46:49], v[158:161], v[202:205], v[46:49]
	v_mfma_f32_16x16x32_bf16 v[58:61], v[158:161], v[194:197], v[58:61]
	v_mfma_f32_16x16x32_bf16 v[58:61], v[154:157], v[190:193], v[58:61]
	s_setprio 0
	s_setprio 1
	v_mfma_f32_16x16x32_bf16 v[50:53], v[162:165], v[190:193], v[50:53]
	v_mfma_f32_16x16x32_bf16 v[50:53], v[166:169], v[194:197], v[50:53]
	v_mfma_f32_16x16x32_bf16 v[34:37], v[166:169], v[202:205], v[34:37]
	v_mfma_f32_16x16x32_bf16 v[34:37], v[162:165], v[198:201], v[34:37]
	v_mfma_f32_16x16x32_bf16 v[18:21], v[162:165], v[206:209], v[18:21]
	v_mfma_f32_16x16x32_bf16 v[18:21], v[166:169], v[228:231], v[18:21]
	v_mfma_f32_16x16x32_bf16 v[6:9], v[166:169], v[236:239], v[6:9]
	v_mfma_f32_16x16x32_bf16 v[6:9], v[162:165], v[232:235], v[6:9]
	v_mfma_f32_16x16x32_bf16 v[2:5], v[170:173], v[232:235], v[2:5]
	v_mfma_f32_16x16x32_bf16 v[2:5], v[178:181], v[236:239], v[2:5]
	v_mfma_f32_16x16x32_bf16 v[10:13], v[178:181], v[228:231], v[10:13]
	v_mfma_f32_16x16x32_bf16 v[10:13], v[170:173], v[206:209], v[10:13]
	v_mfma_f32_16x16x32_bf16 v[26:29], v[170:173], v[198:201], v[26:29]
	v_mfma_f32_16x16x32_bf16 v[26:29], v[178:181], v[202:205], v[26:29]
	v_mfma_f32_16x16x32_bf16 v[42:45], v[178:181], v[194:197], v[42:45]
	v_mfma_f32_16x16x32_bf16 v[42:45], v[170:173], v[190:193], v[42:45]
	s_setprio 0
	s_barrier
	s_add_i32 s49, 0, 0x18000
	s_add_i32 s50, 0, 0x1c000
	v_add_u32_e32 v158, s49, v143
	v_add_u32_e32 v175, s50, v143
	ds_read_b128 v[146:149], v158
	ds_read_b128 v[150:153], v158 offset:1024
	ds_read_b128 v[154:157], v158 offset:2048
	ds_read_b128 v[158:161], v158 offset:3072
	ds_read_b128 v[162:165], v175
	ds_read_b128 v[166:169], v175 offset:1024
	ds_read_b128 v[170:173], v175 offset:2048
	ds_read_b128 v[178:181], v175 offset:3072
	s_add_u32 s14, s22, 0x2b0000
	s_addc_u32 s15, s23, 0
	s_mov_b32 m0, s37
	v_lshl_add_u64 v[226:227], s[14:15], 0, v[134:135]
	ds_read_b128 v[190:193], v145 offset:32768
	ds_read_b128 v[194:197], v145 offset:33792
	ds_read_b128 v[198:201], v145 offset:34816
	ds_read_b128 v[202:205], v145 offset:35840
	ds_read_b128 v[206:209], v145 offset:36864
	ds_read_b128 v[228:231], v145 offset:37888
	ds_read_b128 v[232:235], v145 offset:38912
	ds_read_b128 v[236:239], v145 offset:39936
	global_load_lds_dwordx4 v[226:227], off
	v_lshl_add_u64 v[226:227], s[14:15], 0, v[132:133]
	s_mov_b32 m0, s38
	s_nop 0
	global_load_lds_dwordx4 v[226:227], off
	s_waitcnt vmcnt(8)
	s_waitcnt lgkmcnt(0)
	s_barrier
	s_setprio 1
	s_waitcnt lgkmcnt(0)
	v_mfma_f32_16x16x32_bf16 v[126:129], v[146:149], v[190:193], v[126:129]
	v_mfma_f32_16x16x32_bf16 v[126:129], v[150:153], v[194:197], v[126:129]
	v_mfma_f32_16x16x32_bf16 v[118:121], v[150:153], v[202:205], v[118:121]
	v_mfma_f32_16x16x32_bf16 v[118:121], v[146:149], v[198:201], v[118:121]
	v_mfma_f32_16x16x32_bf16 v[102:105], v[146:149], v[206:209], v[102:105]
	v_mfma_f32_16x16x32_bf16 v[102:105], v[150:153], v[228:231], v[102:105]
	v_mfma_f32_16x16x32_bf16 v[86:89], v[150:153], v[236:239], v[86:89]
	v_mfma_f32_16x16x32_bf16 v[86:89], v[146:149], v[232:235], v[86:89]
	v_mfma_f32_16x16x32_bf16 v[78:81], v[154:157], v[232:235], v[78:81]
	v_mfma_f32_16x16x32_bf16 v[78:81], v[158:161], v[236:239], v[78:81]
	v_mfma_f32_16x16x32_bf16 v[94:97], v[158:161], v[228:231], v[94:97]
	v_mfma_f32_16x16x32_bf16 v[94:97], v[154:157], v[206:209], v[94:97]
	v_mfma_f32_16x16x32_bf16 v[110:113], v[154:157], v[198:201], v[110:113]
	v_mfma_f32_16x16x32_bf16 v[110:113], v[158:161], v[202:205], v[110:113]
	v_mfma_f32_16x16x32_bf16 v[122:125], v[158:161], v[194:197], v[122:125]
	v_mfma_f32_16x16x32_bf16 v[122:125], v[154:157], v[190:193], v[122:125]
	s_setprio 0
	s_setprio 1
	v_mfma_f32_16x16x32_bf16 v[114:117], v[162:165], v[190:193], v[114:117]
	v_mfma_f32_16x16x32_bf16 v[114:117], v[166:169], v[194:197], v[114:117]
	v_mfma_f32_16x16x32_bf16 v[98:101], v[166:169], v[202:205], v[98:101]
	v_mfma_f32_16x16x32_bf16 v[98:101], v[162:165], v[198:201], v[98:101]
	v_mfma_f32_16x16x32_bf16 v[82:85], v[162:165], v[206:209], v[82:85]
	v_mfma_f32_16x16x32_bf16 v[82:85], v[166:169], v[228:231], v[82:85]
	v_mfma_f32_16x16x32_bf16 v[70:73], v[166:169], v[236:239], v[70:73]
	v_mfma_f32_16x16x32_bf16 v[70:73], v[162:165], v[232:235], v[70:73]
	v_mfma_f32_16x16x32_bf16 v[66:69], v[170:173], v[232:235], v[66:69]
	v_mfma_f32_16x16x32_bf16 v[66:69], v[178:181], v[236:239], v[66:69]
	v_mfma_f32_16x16x32_bf16 v[74:77], v[178:181], v[228:231], v[74:77]
	v_mfma_f32_16x16x32_bf16 v[74:77], v[170:173], v[206:209], v[74:77]
	v_mfma_f32_16x16x32_bf16 v[90:93], v[170:173], v[198:201], v[90:93]
	v_mfma_f32_16x16x32_bf16 v[90:93], v[178:181], v[202:205], v[90:93]
	v_mfma_f32_16x16x32_bf16 v[106:109], v[178:181], v[194:197], v[106:109]
	v_mfma_f32_16x16x32_bf16 v[106:109], v[170:173], v[190:193], v[106:109]
	s_setprio 0
	s_barrier
	s_add_i32 s14, s49, s26
	v_lshl_add_u64 v[140:141], v[140:141], 0, s[34:35]
	s_mov_b32 m0, s14
	ds_read_b128 v[190:193], v145 offset:49152
	ds_read_b128 v[194:197], v145 offset:50176
	ds_read_b128 v[198:201], v145 offset:51200
	ds_read_b128 v[202:205], v145 offset:52224
	ds_read_b128 v[206:209], v145 offset:53248
	ds_read_b128 v[228:231], v145 offset:54272
	ds_read_b128 v[232:235], v145 offset:55296
	ds_read_b128 v[236:239], v145 offset:56320
	global_load_lds_dwordx4 v[140:141], off
	s_add_i32 m0, s14, 0x2000
	s_add_u32 s14, s18, 0x2b0080
	v_lshl_add_u64 v[140:141], v[186:187], 0, s[34:35]
	s_addc_u32 s15, s19, 0
	s_add_i32 s18, s50, s26
	global_load_lds_dwordx4 v[140:141], off
	v_lshl_add_u64 v[140:141], s[14:15], 0, v[0:1]
	s_mov_b32 m0, s18
	s_nop 0
	global_load_lds_dwordx4 v[140:141], off
	v_lshl_add_u64 v[140:141], s[14:15], 0, v[130:131]
	s_add_i32 m0, s18, 0x2000
	s_nop 0
	global_load_lds_dwordx4 v[140:141], off
	v_lshl_add_u64 v[140:141], v[188:189], 0, s[34:35]
	s_mov_b32 m0, s39
	s_nop 0
	global_load_lds_dwordx4 v[140:141], off
	v_lshl_add_u64 v[140:141], v[210:211], 0, s[34:35]
	s_mov_b32 m0, s40
	s_nop 0
	global_load_lds_dwordx4 v[140:141], off
	s_waitcnt vmcnt(8)
	s_waitcnt lgkmcnt(0)
	s_barrier
	s_setprio 1
	s_waitcnt lgkmcnt(0)
	v_mfma_f32_16x16x32_bf16 v[62:65], v[146:149], v[190:193], v[62:65]
	v_mfma_f32_16x16x32_bf16 v[62:65], v[150:153], v[194:197], v[62:65]
	v_mfma_f32_16x16x32_bf16 v[54:57], v[150:153], v[202:205], v[54:57]
	v_mfma_f32_16x16x32_bf16 v[54:57], v[146:149], v[198:201], v[54:57]
	v_mfma_f32_16x16x32_bf16 v[38:41], v[146:149], v[206:209], v[38:41]
	v_mfma_f32_16x16x32_bf16 v[38:41], v[150:153], v[228:231], v[38:41]
	v_mfma_f32_16x16x32_bf16 v[22:25], v[150:153], v[236:239], v[22:25]
	v_mfma_f32_16x16x32_bf16 v[22:25], v[146:149], v[232:235], v[22:25]
	v_mfma_f32_16x16x32_bf16 v[14:17], v[154:157], v[232:235], v[14:17]
	v_mfma_f32_16x16x32_bf16 v[14:17], v[158:161], v[236:239], v[14:17]
	v_mfma_f32_16x16x32_bf16 v[30:33], v[158:161], v[228:231], v[30:33]
	v_mfma_f32_16x16x32_bf16 v[30:33], v[154:157], v[206:209], v[30:33]
	v_mfma_f32_16x16x32_bf16 v[46:49], v[154:157], v[198:201], v[46:49]
	v_mfma_f32_16x16x32_bf16 v[46:49], v[158:161], v[202:205], v[46:49]
	v_mfma_f32_16x16x32_bf16 v[58:61], v[158:161], v[194:197], v[58:61]
	v_mfma_f32_16x16x32_bf16 v[58:61], v[154:157], v[190:193], v[58:61]
	s_setprio 0
	s_setprio 1
	v_mfma_f32_16x16x32_bf16 v[50:53], v[162:165], v[190:193], v[50:53]
	v_mfma_f32_16x16x32_bf16 v[50:53], v[166:169], v[194:197], v[50:53]
	v_mfma_f32_16x16x32_bf16 v[34:37], v[166:169], v[202:205], v[34:37]
	v_mfma_f32_16x16x32_bf16 v[34:37], v[162:165], v[198:201], v[34:37]
	v_mfma_f32_16x16x32_bf16 v[18:21], v[162:165], v[206:209], v[18:21]
	v_mfma_f32_16x16x32_bf16 v[18:21], v[166:169], v[228:231], v[18:21]
	v_mfma_f32_16x16x32_bf16 v[6:9], v[166:169], v[236:239], v[6:9]
	v_mfma_f32_16x16x32_bf16 v[6:9], v[162:165], v[232:235], v[6:9]
	v_mfma_f32_16x16x32_bf16 v[2:5], v[170:173], v[232:235], v[2:5]
	v_mfma_f32_16x16x32_bf16 v[2:5], v[178:181], v[236:239], v[2:5]
	v_mfma_f32_16x16x32_bf16 v[10:13], v[178:181], v[228:231], v[10:13]
	v_mfma_f32_16x16x32_bf16 v[10:13], v[170:173], v[206:209], v[10:13]
	v_mfma_f32_16x16x32_bf16 v[26:29], v[170:173], v[198:201], v[26:29]
	v_mfma_f32_16x16x32_bf16 v[26:29], v[178:181], v[202:205], v[26:29]
	v_mfma_f32_16x16x32_bf16 v[42:45], v[178:181], v[194:197], v[42:45]
	v_mfma_f32_16x16x32_bf16 v[42:45], v[170:173], v[190:193], v[42:45]
	s_add_i32 s48, s48, 2
	s_add_u32 s46, s46, 0x100
	s_addc_u32 s47, s47, 0
	s_mov_b64 s[14:15], s[16:17]
	s_add_u32 s16, s14, 0x100
	s_addc_u32 s17, s15, 0
	s_cmpk_eq_i32 s48, 0xa8
	s_cselect_b32 s23, s5, s17
	s_cselect_b32 s22, s4, s16
	s_cselect_b32 s19, s9, s47
	s_cselect_b32 s18, s8, s46
	s_cmpk_gt_u32 s48, 0xa9
	s_setprio 0
	s_barrier
	s_cbranch_scc0 .LBB0_805
	s_and_b64 vcc, exec, s[6:7]
	s_cbranch_vccz .LBB0_808
	s_barrier
